# layer-0 MoE weight conversion (prologue share) hosted in the diff-attention tile loops; pointers cached in SGPRs; trickled nt loads
# speedup vs baseline: 1.0029x; 1.0029x over previous
.LBB0_211:
	s_or_b64 exec, exec, s[6:7]
	v_cvt_f32_u32_e32 v0, s16
	s_sub_i32 s5, 0, s16
	s_add_i32 s4, s16, 0x5fffff
	s_mov_b32 s14, 16
	v_rcp_iflag_f32_e32 v0, v0
	s_nop 0
	v_mul_f32_e32 v0, 0x4f7ffffe, v0
	v_cvt_u32_f32_e32 v0, v0
	s_nop 0
	v_readfirstlane_b32 s6, v0
	s_mul_i32 s5, s5, s6
	s_mul_hi_u32 s5, s6, s5
	s_add_i32 s6, s6, s5
	s_mul_hi_u32 s5, s4, s6
	s_mul_i32 s6, s5, s16
	s_sub_i32 s4, s4, s6
	s_add_i32 s7, s5, 1
	s_sub_i32 s6, s4, s16
	s_cmp_ge_u32 s4, s16
	s_cselect_b32 s5, s7, s5
	s_cselect_b32 s4, s6, s4
	s_add_i32 s6, s5, 1
	s_cmp_ge_u32 s4, s16
	s_cselect_b32 s6, s6, s5
	s_branch .LBB0_234
	s_mul_i32 s7, s3, 0x2200
	s_mul_i32 s8, s3, 0x600
	s_mul_i32 s9, s3, 0x2400
	s_lshl_b32 s10, s3, 13
	s_mov_b32 s13, 16
	v_mov_b32_e32 v71, 0
	s_movk_i32 s11, 0x78
	s_movk_i32 s12, 0xf8
	v_mov_b32_e32 v69, 0x80
	v_mov_b32_e32 v83, 0x138
	v_mov_b32_e32 v84, 0x130

.LBB0_1443:
	s_cmp_gt_i32 s40, 4
	s_cselect_b64 s[4:5], -1, 0
	s_cmp_lt_i32 s41, 5
	s_cselect_b64 s[6:7], -1, 0
	s_or_b64 s[4:5], s[4:5], s[6:7]
	s_and_b64 vcc, exec, s[4:5]
	s_cbranch_vccnz .LBB0_1517
	s_waitcnt lgkmcnt(0)
	s_mov_b64 s[20:21], s[0:1]
	s_load_dwordx8 s[4:11], s[20:21], 0x50
	s_load_dwordx4 s[12:15], s[20:21], 0x70
	s_load_dwordx4 s[16:19], s[20:21], 0x88
	v_mbcnt_lo_u32_b32 v0, -1, 0
	v_mbcnt_hi_u32_b32 v0, -1, v0
	v_and_b32_e32 v1, 63, v0
	v_lshlrev_b32_e32 v1, 2, v1
	s_waitcnt lgkmcnt(0)
	global_load_dword v2, v1, s[4:5]
	global_load_dword v3, v1, s[6:7]
	global_load_dword v4, v1, s[16:17] offset:256
	global_load_dword v5, v1, s[18:19] offset:256
	global_load_dword v6, v1, s[16:17]
	global_load_dword v7, v1, s[18:19]
	global_load_dword v8, v1, s[8:9]
	global_load_dword v9, v1, s[10:11]
	global_load_dword v10, v1, s[12:13]
	global_load_dword v11, v1, s[14:15]
	v_and_b32_e32 v1, 64, v0
	v_xor_b32_e32 v12, 32, v0
	v_add_u32_e32 v1, 64, v1
	v_xor_b32_e32 v13, 16, v0
	v_cmp_lt_i32_e32 vcc, v12, v1
	v_xor_b32_e32 v14, 8, v0
	v_xor_b32_e32 v15, 4, v0
	v_cndmask_b32_e32 v12, v0, v12, vcc
	v_cmp_lt_i32_e32 vcc, v13, v1
	v_xor_b32_e32 v16, 2, v0
	v_xor_b32_e32 v17, 1, v0
	v_cndmask_b32_e32 v13, v0, v13, vcc
	v_cmp_lt_i32_e32 vcc, v14, v1
	v_lshlrev_b32_e32 v133, 2, v12
	v_lshlrev_b32_e32 v12, 2, v13
	v_cndmask_b32_e32 v14, v0, v14, vcc
	v_cmp_lt_i32_e32 vcc, v15, v1
	v_lshlrev_b32_e32 v13, 2, v14
	s_mov_b32 s5, 0
	v_cndmask_b32_e32 v15, v0, v15, vcc
	v_cmp_lt_i32_e32 vcc, v16, v1
	v_lshlrev_b32_e32 v14, 2, v15
	s_cmpk_gt_i32 s2, 0x1ff
	v_cndmask_b32_e32 v16, v0, v16, vcc
	v_cmp_lt_i32_e32 vcc, v17, v1
	v_lshlrev_b32_e32 v15, 2, v16
	s_waitcnt vmcnt(0)
	v_max_f32_e64 v4, |v4|, |v4|
	v_cndmask_b32_e32 v1, v0, v17, vcc
	v_lshlrev_b32_e32 v16, 2, v1
	v_and_b32_e32 v1, 0x7fffffff, v2
	v_and_b32_e32 v17, 0x7fffffff, v3
	v_max_f32_e64 v6, |v6|, |v6|
	v_max_f32_e64 v5, |v5|, |v5|
	v_max_f32_e64 v7, |v7|, |v7|
	v_mul_f32_e32 v18, v8, v9
	v_mul_f32_e32 v19, v10, v11
	ds_bpermute_b32 v1, v133, v1
	ds_bpermute_b32 v17, v133, v17
	v_max_f32_e32 v4, v6, v4
	v_max_f32_e32 v5, v7, v5
	ds_bpermute_b32 v6, v133, v18
	ds_bpermute_b32 v7, v133, v19
	ds_bpermute_b32 v18, v133, v4
	ds_bpermute_b32 v19, v133, v5
	v_max_f32_e64 v2, |v2|, |v2|
	v_max_f32_e64 v3, |v3|, |v3|
	s_waitcnt lgkmcnt(5)
	v_max_f32_e32 v1, v1, v1
	s_waitcnt lgkmcnt(4)
	v_max_f32_e32 v17, v17, v17
	s_waitcnt lgkmcnt(3)
	v_fmac_f32_e32 v6, v8, v9
	s_waitcnt lgkmcnt(2)
	v_fmac_f32_e32 v7, v10, v11
	v_max_f32_e32 v1, v2, v1
	v_max_f32_e32 v2, v3, v17
	s_waitcnt lgkmcnt(1)
	v_max_f32_e32 v3, v18, v18
	s_waitcnt lgkmcnt(0)
	v_max_f32_e32 v8, v19, v19
	ds_bpermute_b32 v9, v12, v6
	ds_bpermute_b32 v10, v12, v7
	ds_bpermute_b32 v11, v12, v1
	ds_bpermute_b32 v17, v12, v2
	v_max_f32_e32 v3, v4, v3
	v_max_f32_e32 v4, v5, v8
	ds_bpermute_b32 v5, v12, v3
	ds_bpermute_b32 v8, v12, v4
	s_waitcnt lgkmcnt(5)
	v_add_f32_e32 v6, v6, v9
	s_waitcnt lgkmcnt(4)
	v_add_f32_e32 v7, v7, v10
	s_waitcnt lgkmcnt(3)
	v_max_f32_e32 v9, v11, v11
	s_waitcnt lgkmcnt(2)
	v_max_f32_e32 v10, v17, v17
	v_max_f32_e32 v1, v1, v9
	v_max_f32_e32 v2, v2, v10
	s_waitcnt lgkmcnt(1)
	v_max_f32_e32 v5, v5, v5
	s_waitcnt lgkmcnt(0)
	v_max_f32_e32 v8, v8, v8
	ds_bpermute_b32 v9, v13, v1
	ds_bpermute_b32 v10, v13, v2
	v_max_f32_e32 v3, v3, v5
	v_max_f32_e32 v4, v4, v8
	ds_bpermute_b32 v5, v13, v3
	ds_bpermute_b32 v8, v13, v4
	s_waitcnt lgkmcnt(3)
	v_max_f32_e32 v9, v9, v9
	s_waitcnt lgkmcnt(2)
	v_max_f32_e32 v10, v10, v10
	v_max_f32_e32 v1, v1, v9
	v_max_f32_e32 v2, v2, v10
	s_waitcnt lgkmcnt(1)
	v_max_f32_e32 v5, v5, v5
	s_waitcnt lgkmcnt(0)
	v_max_f32_e32 v8, v8, v8
	ds_bpermute_b32 v9, v14, v1
	ds_bpermute_b32 v10, v14, v2
	v_max_f32_e32 v3, v3, v5
	v_max_f32_e32 v5, v4, v8
	ds_bpermute_b32 v4, v14, v3
	s_waitcnt lgkmcnt(2)
	v_max_f32_e32 v9, v9, v9
	s_waitcnt lgkmcnt(1)
	v_max_f32_e32 v10, v10, v10
	v_max_f32_e32 v1, v1, v9
	v_max_f32_e32 v9, v2, v10
	s_waitcnt lgkmcnt(0)
	v_max_f32_e32 v2, v4, v4
	ds_bpermute_b32 v11, v13, v6
	ds_bpermute_b32 v12, v13, v7
	ds_bpermute_b32 v4, v15, v1
	ds_bpermute_b32 v10, v15, v9
	v_max_f32_e32 v13, v3, v2
	ds_bpermute_b32 v3, v15, v13
	ds_bpermute_b32 v8, v14, v5
	s_waitcnt lgkmcnt(3)
	v_max_f32_e32 v2, v4, v4
	s_waitcnt lgkmcnt(2)
	v_max_f32_e32 v4, v10, v10
	v_max_f32_e32 v2, v1, v2
	v_max_f32_e32 v1, v9, v4
	s_waitcnt lgkmcnt(1)
	v_max_f32_e32 v9, v3, v3
	v_add_f32_e32 v6, v6, v11
	v_add_f32_e32 v7, v7, v12
	v_max_f32_e32 v129, v13, v9
	ds_bpermute_b32 v9, v14, v6
	ds_bpermute_b32 v10, v14, v7
	s_waitcnt lgkmcnt(2)
	v_max_f32_e32 v8, v8, v8
	v_max_f32_e32 v5, v5, v8
	ds_bpermute_b32 v8, v15, v5
	s_waitcnt lgkmcnt(2)
	v_add_f32_e32 v6, v6, v9
	s_waitcnt lgkmcnt(1)
	v_add_f32_e32 v7, v7, v10
	ds_bpermute_b32 v9, v15, v6
	ds_bpermute_b32 v10, v15, v7
	s_waitcnt lgkmcnt(2)
	v_max_f32_e32 v8, v8, v8
	v_max_f32_e32 v172, v5, v8
	ds_bpermute_b32 v4, v16, v2
	s_waitcnt lgkmcnt(2)
	v_add_f32_e32 v8, v6, v9
	s_waitcnt lgkmcnt(1)
	v_add_f32_e32 v6, v7, v10
	ds_bpermute_b32 v3, v16, v1
	ds_bpermute_b32 v171, v16, v129
	ds_bpermute_b32 v173, v16, v172
	ds_bpermute_b32 v9, v16, v8
	ds_bpermute_b32 v7, v16, v6
	v_add_u32_e32 v5, s63, v0
	s_nop 0
	v_readfirstlane_b32 s3, v5
	s_cbranch_scc1 .LBB0_1467
	s_waitcnt lgkmcnt(1)
	v_add_f32_e32 v8, v8, v9
	s_mov_b32 s4, 0x3fb8aa3b
	v_mul_f32_e32 v9, 0x3fb8aa3b, v8
	v_fma_f32 v10, v8, s4, -v9
	v_rndne_f32_e32 v11, v9
	v_fmac_f32_e32 v10, 0x32a5705f, v8
	v_sub_f32_e32 v9, v9, v11
	v_add_f32_e32 v9, v9, v10
	v_exp_f32_e32 v9, v9
	v_cvt_i32_f32_e32 v10, v11
	s_waitcnt lgkmcnt(0)
	v_add_f32_e32 v6, v6, v7
	v_mul_f32_e32 v7, 0x3fb8aa3b, v6
	v_rndne_f32_e32 v11, v7
	v_ldexp_f32 v9, v9, v10
	v_fma_f32 v10, v6, s4, -v7
	v_fmac_f32_e32 v10, 0x32a5705f, v6
	v_sub_f32_e32 v7, v7, v11
	v_add_f32_e32 v7, v7, v10
	v_exp_f32_e32 v7, v7
	v_cvt_i32_f32_e32 v10, v11
	s_mov_b32 s6, 0xc2ce8ed0
	v_cmp_ngt_f32_e32 vcc, s6, v8
	s_mov_b32 s7, 0x42b17218
	v_mov_b32_e32 v11, 0x7f800000
	v_cndmask_b32_e32 v9, 0, v9, vcc
	v_cmp_nlt_f32_e32 vcc, s7, v8
	v_ldexp_f32 v7, v7, v10
	v_max_f32_e32 v4, v4, v4
	v_cndmask_b32_e32 v8, v11, v9, vcc
	v_cmp_ngt_f32_e32 vcc, s6, v6
	v_max_f32_e32 v2, v2, v2
	v_max_f32_e32 v2, v2, v4
	v_cndmask_b32_e32 v7, 0, v7, vcc
	v_cmp_nlt_f32_e32 vcc, s7, v6
	v_mul_f32_e32 v2, 0x3fb8aa3b, v2
	v_max_f32_e32 v3, v3, v3
	v_cndmask_b32_e32 v6, v11, v7, vcc
	v_max_f32_e32 v1, v1, v1
	v_sub_f32_e32 v6, v8, v6
	v_mul_f32_e32 v2, 0x41000000, v2
	v_max_f32_e32 v1, v1, v3
	v_add_f32_e32 v136, 0x3e4ccccd, v6
	v_and_b32_e32 v6, 0xff, v5
	v_mul_f32_e32 v1, v2, v1
	v_and_b32_e32 v174, 31, v0
	v_bfe_u32 v2, v5, 5, 3
	v_lshrrev_b32_e32 v3, 1, v5
	s_load_dwordx4 s[28:31], s[20:21], 0x1d8
	s_ashr_i32 s3, s3, 8
	v_bfe_u32 v17, v6, 5, 1
	v_and_b32_e32 v175, 0x60, v3
	v_bitop3_b32 v3, v2, v174, 1 bitop3:0x6c
	s_lshl_b32 s4, s3, 12
	v_lshlrev_b32_e32 v128, 4, v6
	v_lshlrev_b32_e32 v177, 4, v3
	v_bitop3_b32 v3, v17, v174, 2 bitop3:0x36
	v_bitop3_b32 v2, v2, v174, 6 bitop3:0x36
	v_or_b32_e32 v138, s4, v128
	v_lshlrev_b32_e32 v178, 4, v3
	v_bitop3_b32 v3, v17, v174, 4 bitop3:0x36
	v_lshlrev_b32_e32 v180, 4, v2
	v_bfe_u32 v2, v0, 3, 2
	v_lshlrev_b32_e32 v179, 4, v3
	v_lshlrev_b32_e32 v3, 11, v17
	v_bitop3_b32 v0, v2, v0, 31 bitop3:0x78
	v_ashrrev_i32_e32 v139, 31, v138
	v_lshl_or_b32 v168, v0, 4, v3
	v_bitop3_b32 v0, v2, v174, 4 bitop3:0x36
	s_waitcnt lgkmcnt(0)
	v_lshl_add_u64 v[140:141], s[28:29], 0, v[138:139]
	s_mov_b64 s[8:9], 0x220c000
	s_lshl_b32 s36, s3, 1
	v_lshl_or_b32 v169, v0, 4, v3
	v_mov_b32_e32 v0, 0xfffffc00
	v_lshl_add_u64 v[142:143], v[140:141], 0, s[8:9]
	s_mov_b64 s[8:9], 0x6000
	v_lshlrev_b32_e32 v16, 3, v17
	v_bitop3_b32 v181, s4, v0, v128 bitop3:0xc8
	v_mul_f32_e32 v0, 0xbf828f5c, v1
	s_add_u32 s6, s0, 0x230
	v_lshl_add_u64 v[144:145], v[140:141], 0, s[8:9]
	s_mov_b64 s[8:9], 0x226000
	v_mov_b32_e32 v131, 0
	v_lshlrev_b32_e32 v176, 10, v17
	v_add_u32_e32 v182, 0, v181
	v_mov_b32_e32 v1, v0
	v_mov_b32_e32 v2, v0
	v_mov_b32_e32 v3, v0
	v_mov_b32_e32 v4, v0
	v_mov_b32_e32 v5, v0
	v_mov_b32_e32 v6, v0
	v_mov_b32_e32 v7, v0
	v_mov_b32_e32 v8, v0
	v_mov_b32_e32 v9, v0
	v_mov_b32_e32 v10, v0
	v_mov_b32_e32 v11, v0
	v_mov_b32_e32 v12, v0
	v_mov_b32_e32 v13, v0
	v_mov_b32_e32 v14, v0
	v_mov_b32_e32 v15, v0
	v_lshlrev_b32_e32 v132, 2, v17
	s_addc_u32 s7, s1, 0
	v_mov_b32_e32 v137, v136
	v_or_b32_e32 v170, v175, v174
	v_lshl_add_u64 v[146:147], v[140:141], 0, s[8:9]
	s_movk_i32 s37, 0x2400
	s_mov_b64 s[8:9], 0x2200000
	s_mov_b64 s[10:11], 0x2000
	s_add_i32 s42, 0, 0x10000
	s_add_i32 s43, 0, 0x14000
	s_add_i32 s44, 0, 0x16000
	s_mov_b64 s[12:13], 0x4000
	v_lshlrev_b32_e32 v134, 1, v16
	v_mov_b32_e32 v183, 0x358637bd
	s_mov_b32 s45, 0x800000
	s_mov_b32 s46, s2
	s_mov_b32 s98, 16
	s_load_dwordx4 s[76:79], s[0:1], 0x130
	s_load_dwordx2 s[80:81], s[0:1], 0x140
	s_load_dwordx4 s[84:87], s[0:1], 0x1c0
	s_waitcnt lgkmcnt(0)
	s_branch .LBB0_1447
.LBB0_1446:
	ds_bpermute_b32 v80, v133, v135
	v_lshlrev_b32_e32 v104, 2, v132
	s_lshl_b64 s[14:15], s[14:15], 24
	v_lshlrev_b32_e32 v130, 12, v130
	s_waitcnt lgkmcnt(0)
	v_add_f32_e32 v80, v135, v80
	v_div_scale_f32 v81, s[16:17], v80, v80, 1.0
	v_rcp_f32_e32 v82, v81
	v_div_scale_f32 v83, vcc, 1.0, v80, 1.0
	s_load_dwordx2 s[16:17], s[20:21], 0x80
	v_fma_f32 v84, -v81, v82, 1.0
	v_fmac_f32_e32 v82, v84, v82
	v_mul_f32_e32 v84, v83, v82
	v_fma_f32 v85, -v81, v84, v83
	v_fmac_f32_e32 v84, v85, v82
	v_fma_f32 v81, -v81, v84, v83
	v_div_fmas_f32 v81, v81, v82, v84
	v_div_fixup_f32 v80, v81, v80, 1.0
	v_mul_f32_e32 v66, v66, v80
	v_lshlrev_b32_e32 v83, 16, v214
	v_mul_f32_e32 v65, v65, v80
	v_mul_f32_e32 v69, v69, v80
	v_and_b32_e32 v82, 0xffff0000, v216
	v_fma_f32 v122, -v136, v66, v83
	v_and_b32_e32 v66, 0xffff0000, v212
	v_mul_f32_e32 v64, v64, v80
	v_mul_f32_e32 v67, v67, v80
	v_mul_f32_e32 v68, v68, v80
	v_lshlrev_b32_e32 v81, 16, v216
	v_and_b32_e32 v84, 0xffff0000, v214
	v_fma_f32 v121, -v136, v65, v82
	v_lshlrev_b32_e32 v65, 16, v212
	v_fma_f32 v125, -v136, v69, v66
	v_mul_f32_e32 v70, v70, v80
	v_fma_f32 v120, -v136, v64, v81
	v_fma_f32 v123, -v136, v67, v84
	v_mul_f32_e32 v64, v121, v121
	v_lshlrev_b32_e32 v67, 16, v210
	v_fma_f32 v124, -v136, v68, v65
	v_mul_f32_e32 v65, v125, v125
	v_mul_f32_e32 v71, v71, v80
	v_fmac_f32_e32 v64, v120, v120
	v_and_b32_e32 v81, 0xffff0000, v210
	v_fma_f32 v126, -v136, v70, v67
	v_fmac_f32_e32 v65, v124, v124
	v_fmac_f32_e32 v64, v122, v122
	v_fma_f32 v127, -v136, v71, v81
	v_fmac_f32_e32 v65, v126, v126
	v_mul_f32_e32 v73, v73, v80
	v_fmac_f32_e32 v64, v123, v123
	v_fmac_f32_e32 v65, v127, v127
	v_and_b32_e32 v66, 0xffff0000, v207
	v_mul_f32_e32 v72, v72, v80
	v_add_f32_e32 v64, v64, v65
	v_lshlrev_b32_e32 v65, 16, v207
	v_fma_f32 v148, -v136, v73, v66
	v_mul_f32_e32 v74, v74, v80
	v_lshlrev_b32_e32 v67, 16, v206
	v_fma_f32 v135, -v136, v72, v65
	v_mul_f32_e32 v65, v148, v148
	v_mul_f32_e32 v75, v75, v80
	v_and_b32_e32 v68, 0xffff0000, v206
	v_fma_f32 v149, -v136, v74, v67
	v_fmac_f32_e32 v65, v135, v135
	v_fma_f32 v150, -v136, v75, v68
	v_fmac_f32_e32 v65, v149, v149
	v_mul_f32_e32 v77, v77, v80
	v_fmac_f32_e32 v65, v150, v150
	v_and_b32_e32 v66, 0xffff0000, v205
	v_mul_f32_e32 v76, v76, v80
	v_add_f32_e32 v64, v65, v64
	v_lshlrev_b32_e32 v65, 16, v205
	v_fma_f32 v152, -v136, v77, v66
	v_mul_f32_e32 v78, v78, v80
	v_lshlrev_b32_e32 v67, 16, v204
	v_fma_f32 v151, -v136, v76, v65
	v_mul_f32_e32 v65, v152, v152
	v_mul_f32_e32 v79, v79, v80
	v_and_b32_e32 v68, 0xffff0000, v204
	v_fma_f32 v153, -v136, v78, v67
	v_fmac_f32_e32 v65, v151, v151
	v_fma_f32 v154, -v136, v79, v68
	v_fmac_f32_e32 v65, v153, v153
	v_mul_f32_e32 v49, v49, v80
	v_fmac_f32_e32 v65, v154, v154
	v_and_b32_e32 v66, 0xffff0000, v203
	v_mul_f32_e32 v48, v48, v80
	v_add_f32_e32 v64, v65, v64
	v_lshlrev_b32_e32 v65, 16, v203
	v_fma_f32 v156, -v136, v49, v66
	v_mul_f32_e32 v50, v50, v80
	v_lshlrev_b32_e32 v67, 16, v202
	v_fma_f32 v155, -v136, v48, v65
	v_mul_f32_e32 v48, v156, v156
	v_mul_f32_e32 v51, v51, v80
	v_mul_f32_e32 v53, v53, v80
	v_and_b32_e32 v68, 0xffff0000, v202
	v_fma_f32 v157, -v136, v50, v67
	v_fmac_f32_e32 v48, v155, v155
	v_and_b32_e32 v50, 0xffff0000, v201
	v_mul_f32_e32 v52, v52, v80
	v_fma_f32 v158, -v136, v51, v68
	v_fmac_f32_e32 v48, v157, v157
	v_lshlrev_b32_e32 v49, 16, v201
	v_fma_f32 v160, -v136, v53, v50
	v_mul_f32_e32 v54, v54, v80
	v_fmac_f32_e32 v48, v158, v158
	v_lshlrev_b32_e32 v51, 16, v200
	v_fma_f32 v159, -v136, v52, v49
	v_mul_f32_e32 v49, v160, v160
	v_mul_f32_e32 v55, v55, v80
	v_add_f32_e32 v48, v48, v64
	v_and_b32_e32 v64, 0xffff0000, v200
	v_fma_f32 v161, -v136, v54, v51
	v_fmac_f32_e32 v49, v159, v159
	v_fma_f32 v162, -v136, v55, v64
	v_fmac_f32_e32 v49, v161, v161
	v_fmac_f32_e32 v49, v162, v162
	v_mov_b32_e32 v52, v60
	v_mov_b32_e32 v53, v56
	v_mov_b32_e32 v56, v61
	v_add_f32_e32 v68, v49, v48
	v_lshlrev_b32_e32 v49, 16, v197
	v_lshlrev_b32_e32 v48, 16, v199
	v_and_b32_e32 v51, 0xffff0000, v197
	v_and_b32_e32 v50, 0xffff0000, v199
	v_pk_mul_f32 v[52:53], v[52:53], v[80:81] op_sel_hi:[1,0]
	v_pk_mul_f32 v[56:57], v[56:57], v[80:81] op_sel_hi:[1,0]
	v_mov_b32_e32 v54, v62
	v_mov_b32_e32 v55, v58
	v_pk_mul_f32 v[60:61], v[54:55], v[80:81] op_sel_hi:[1,0]
	v_pk_fma_f32 v[54:55], v[136:137], v[52:53], v[48:49] neg_lo:[1,0,0] neg_hi:[1,0,0]
	v_pk_fma_f32 v[52:53], v[136:137], v[56:57], v[50:51] neg_lo:[1,0,0] neg_hi:[1,0,0]
	v_lshlrev_b32_e32 v65, 16, v196
	v_lshlrev_b32_e32 v64, 16, v198
	v_mov_b32_e32 v58, v63
	v_pk_mul_f32 v[56:57], v[52:53], v[52:53]
	v_and_b32_e32 v67, 0xffff0000, v196
	v_and_b32_e32 v66, 0xffff0000, v198
	v_pk_mul_f32 v[58:59], v[58:59], v[80:81] op_sel_hi:[1,0]
	v_pk_fma_f32 v[50:51], v[136:137], v[60:61], v[64:65] neg_lo:[1,0,0] neg_hi:[1,0,0]
	v_pk_fma_f32 v[56:57], v[54:55], v[54:55], v[56:57]
	v_pk_fma_f32 v[48:49], v[136:137], v[58:59], v[66:67] neg_lo:[1,0,0] neg_hi:[1,0,0]
	v_pk_fma_f32 v[56:57], v[50:51], v[50:51], v[56:57]
	v_mov_b32_e32 v65, v32
	v_pk_fma_f32 v[56:57], v[48:49], v[48:49], v[56:57]
	v_mov_b32_e32 v32, v37
	v_add_f32_e32 v57, v57, v68
	v_and_b32_e32 v59, 0xffff0000, v193
	v_and_b32_e32 v58, 0xffff0000, v195
	v_mov_b32_e32 v64, v36
	v_pk_mul_f32 v[32:33], v[32:33], v[80:81] op_sel_hi:[1,0]
	v_mov_b32_e32 v36, v38
	v_mov_b32_e32 v37, v34
	v_add_f32_e32 v70, v56, v57
	v_lshlrev_b32_e32 v57, 16, v193
	v_lshlrev_b32_e32 v56, 16, v195
	v_pk_mul_f32 v[64:65], v[64:65], v[80:81] op_sel_hi:[1,0]
	v_pk_mul_f32 v[66:67], v[36:37], v[80:81] op_sel_hi:[1,0]
	v_pk_fma_f32 v[36:37], v[136:137], v[32:33], v[58:59] neg_lo:[1,0,0] neg_hi:[1,0,0]
	v_lshlrev_b32_e32 v61, 16, v192
	v_lshlrev_b32_e32 v60, 16, v194
	v_mov_b32_e32 v34, v39
	v_pk_fma_f32 v[38:39], v[136:137], v[64:65], v[56:57] neg_lo:[1,0,0] neg_hi:[1,0,0]
	v_pk_mul_f32 v[56:57], v[36:37], v[36:37]
	v_and_b32_e32 v63, 0xffff0000, v192
	v_and_b32_e32 v62, 0xffff0000, v194
	v_pk_mul_f32 v[68:69], v[34:35], v[80:81] op_sel_hi:[1,0]
	v_pk_fma_f32 v[34:35], v[136:137], v[66:67], v[60:61] neg_lo:[1,0,0] neg_hi:[1,0,0]
	v_pk_fma_f32 v[56:57], v[38:39], v[38:39], v[56:57]
	v_pk_fma_f32 v[32:33], v[136:137], v[68:69], v[62:63] neg_lo:[1,0,0] neg_hi:[1,0,0]
	v_pk_fma_f32 v[56:57], v[34:35], v[34:35], v[56:57]
	v_mov_b32_e32 v65, v40
	v_pk_fma_f32 v[56:57], v[32:33], v[32:33], v[56:57]
	v_mov_b32_e32 v40, v45
	v_add_f32_e32 v57, v57, v70
	v_and_b32_e32 v59, 0xffff0000, v189
	v_and_b32_e32 v58, 0xffff0000, v191
	v_mov_b32_e32 v64, v44
	v_pk_mul_f32 v[40:41], v[40:41], v[80:81] op_sel_hi:[1,0]
	v_mov_b32_e32 v44, v46
	v_mov_b32_e32 v45, v42
	v_add_f32_e32 v70, v56, v57
	v_lshlrev_b32_e32 v57, 16, v189
	v_lshlrev_b32_e32 v56, 16, v191
	v_pk_mul_f32 v[64:65], v[64:65], v[80:81] op_sel_hi:[1,0]
	v_pk_mul_f32 v[66:67], v[44:45], v[80:81] op_sel_hi:[1,0]
	v_pk_fma_f32 v[44:45], v[136:137], v[40:41], v[58:59] neg_lo:[1,0,0] neg_hi:[1,0,0]
	v_lshlrev_b32_e32 v61, 16, v188
	v_lshlrev_b32_e32 v60, 16, v190
	v_mov_b32_e32 v42, v47
	v_pk_fma_f32 v[46:47], v[136:137], v[64:65], v[56:57] neg_lo:[1,0,0] neg_hi:[1,0,0]
	v_pk_mul_f32 v[56:57], v[44:45], v[44:45]
	v_and_b32_e32 v63, 0xffff0000, v188
	v_and_b32_e32 v62, 0xffff0000, v190
	v_pk_mul_f32 v[68:69], v[42:43], v[80:81] op_sel_hi:[1,0]
	v_pk_fma_f32 v[42:43], v[136:137], v[66:67], v[60:61] neg_lo:[1,0,0] neg_hi:[1,0,0]
	v_pk_fma_f32 v[56:57], v[46:47], v[46:47], v[56:57]
	v_pk_fma_f32 v[40:41], v[136:137], v[68:69], v[62:63] neg_lo:[1,0,0] neg_hi:[1,0,0]
	v_pk_fma_f32 v[56:57], v[42:43], v[42:43], v[56:57]
	v_mov_b32_e32 v69, v16
	v_pk_fma_f32 v[56:57], v[40:41], v[40:41], v[56:57]
	v_mov_b32_e32 v16, v21
	v_add_f32_e32 v57, v57, v70
	v_add_f32_e32 v70, v56, v57
	s_waitcnt lgkmcnt(0)
	global_load_dwordx4 v[56:59], v104, s[16:17]
	v_and_b32_e32 v63, 0xffff0000, v186
	v_and_b32_e32 v62, 0xffff0000, v187
	v_mov_b32_e32 v68, v20
	v_pk_mul_f32 v[16:17], v[16:17], v[80:81] op_sel_hi:[1,0]
	v_mov_b32_e32 v20, v22
	v_mov_b32_e32 v21, v18
	v_lshlrev_b32_e32 v61, 16, v186
	v_lshlrev_b32_e32 v60, 16, v187
	v_lshlrev_b32_e32 v65, 16, v185
	v_lshlrev_b32_e32 v64, 16, v184
	v_pk_mul_f32 v[68:69], v[68:69], v[80:81] op_sel_hi:[1,0]
	v_pk_mul_f32 v[20:21], v[20:21], v[80:81] op_sel_hi:[1,0]
	v_mov_b32_e32 v18, v23
	v_pk_fma_f32 v[110:111], v[136:137], v[16:17], v[62:63] neg_lo:[1,0,0] neg_hi:[1,0,0]
	v_pk_mul_f32 v[22:23], v[18:19], v[80:81] op_sel_hi:[1,0]
	v_pk_fma_f32 v[108:109], v[136:137], v[68:69], v[60:61] neg_lo:[1,0,0] neg_hi:[1,0,0]
	v_pk_fma_f32 v[18:19], v[136:137], v[20:21], v[64:65] neg_lo:[1,0,0] neg_hi:[1,0,0]
	v_pk_mul_f32 v[20:21], v[110:111], v[110:111]
	v_and_b32_e32 v67, 0xffff0000, v185
	v_and_b32_e32 v66, 0xffff0000, v184
	v_pk_fma_f32 v[20:21], v[108:109], v[108:109], v[20:21]
	v_pk_fma_f32 v[16:17], v[136:137], v[22:23], v[66:67] neg_lo:[1,0,0] neg_hi:[1,0,0]
	v_pk_fma_f32 v[20:21], v[18:19], v[18:19], v[20:21]
	v_mov_b32_e32 v61, v24
	v_pk_fma_f32 v[20:21], v[16:17], v[16:17], v[20:21]
	v_mov_b32_e32 v24, v29
	v_add_f32_e32 v21, v21, v70
	v_add_f32_e32 v74, v20, v21
	global_load_dwordx4 v[20:23], v104, s[16:17] offset:32
	v_and_b32_e32 v67, 0xffff0000, v165
	v_and_b32_e32 v66, 0xffff0000, v167
	v_mov_b32_e32 v60, v28
	v_pk_mul_f32 v[24:25], v[24:25], v[80:81] op_sel_hi:[1,0]
	v_lshlrev_b32_e32 v65, 16, v165
	v_lshlrev_b32_e32 v64, 16, v167
	v_pk_mul_f32 v[72:73], v[60:61], v[80:81] op_sel_hi:[1,0]
	v_mov_b32_e32 v28, v30
	v_mov_b32_e32 v29, v26
	v_pk_fma_f32 v[114:115], v[136:137], v[24:25], v[66:67] neg_lo:[1,0,0] neg_hi:[1,0,0]
	v_lshlrev_b32_e32 v69, 16, v164
	v_lshlrev_b32_e32 v68, 16, v166
	v_pk_mul_f32 v[28:29], v[28:29], v[80:81] op_sel_hi:[1,0]
	v_mov_b32_e32 v26, v31
	v_pk_fma_f32 v[112:113], v[136:137], v[72:73], v[64:65] neg_lo:[1,0,0] neg_hi:[1,0,0]
	v_pk_mul_f32 v[24:25], v[114:115], v[114:115]
	v_and_b32_e32 v71, 0xffff0000, v164
	v_and_b32_e32 v70, 0xffff0000, v166
	global_load_dwordx4 v[60:63], v104, s[16:17] offset:64
	v_pk_mul_f32 v[26:27], v[26:27], v[80:81] op_sel_hi:[1,0]
	v_pk_fma_f32 v[116:117], v[136:137], v[28:29], v[68:69] neg_lo:[1,0,0] neg_hi:[1,0,0]
	v_pk_fma_f32 v[28:29], v[112:113], v[112:113], v[24:25]
	v_pk_fma_f32 v[118:119], v[136:137], v[26:27], v[70:71] neg_lo:[1,0,0] neg_hi:[1,0,0]
	v_pk_fma_f32 v[28:29], v[116:117], v[116:117], v[28:29]
	global_load_dwordx4 v[24:27], v104, s[16:17] offset:96
	v_pk_fma_f32 v[28:29], v[118:119], v[118:119], v[28:29]
	s_nop 0
	v_add_f32_e32 v29, v29, v74
	v_add_f32_e32 v28, v28, v29
	ds_bpermute_b32 v29, v133, v28
	s_waitcnt lgkmcnt(0)
	v_add_f32_e32 v64, v28, v29
	global_load_dwordx4 v[28:31], v104, s[16:17] offset:128
	v_fmamk_f32 v64, v64, 0x3c000000, v183
	v_mul_f32_e32 v65, 0x4b800000, v64
	v_cmp_gt_f32_e32 vcc, s45, v64
	s_nop 1
	v_cndmask_b32_e32 v64, v64, v65, vcc
	v_rsq_f32_e32 v64, v64
	s_nop 0
	v_mul_f32_e32 v65, 0x45800000, v64
	v_cndmask_b32_e32 v163, v64, v65, vcc
	global_load_dwordx4 v[64:67], v104, s[16:17] offset:160
	global_load_dwordx4 v[68:71], v104, s[16:17] offset:192
	global_load_dwordx4 v[72:75], v104, s[16:17] offset:224
	global_load_dwordx4 v[76:79], v104, s[16:17] offset:256
	global_load_dwordx4 v[80:83], v104, s[16:17] offset:288
	global_load_dwordx4 v[84:87], v104, s[16:17] offset:320
	global_load_dwordx4 v[88:91], v104, s[16:17] offset:352
	global_load_dwordx4 v[92:95], v104, s[16:17] offset:384
	global_load_dwordx4 v[96:99], v104, s[16:17] offset:416
	global_load_dwordx4 v[100:103], v104, s[16:17] offset:448
	s_nop 0
	global_load_dwordx4 v[104:107], v104, s[16:17] offset:480
	v_mul_f32_e32 v163, 0x3f4ccccd, v163
	v_mul_f32_e32 v120, v120, v163
	s_waitcnt vmcnt(0)
	v_mul_f32_e32 v56, v56, v120
	v_mul_f32_e32 v120, v121, v163
	v_mul_f32_e32 v57, v57, v120
	v_cvt_pk_bf16_f32 v56, v56, v57
	v_mul_f32_e32 v57, v122, v163
	v_mul_f32_e32 v57, v58, v57
	v_mul_f32_e32 v58, v123, v163
	v_mul_f32_e32 v58, v59, v58
	v_cvt_pk_bf16_f32 v57, v57, v58
	s_load_dwordx2 s[26:27], s[20:21], 0x1f0
	v_mul_f32_e32 v17, v17, v163
	v_mul_f32_e32 v19, v19, v163
	v_mul_f32_e32 v16, v16, v163
	s_waitcnt lgkmcnt(0)
	s_add_u32 s14, s26, s14
	s_addc_u32 s15, s27, s15
	v_lshl_add_u64 v[58:59], s[14:15], 0, v[130:131]
	s_lshl_b32 s4, s47, 1
	v_lshl_add_u64 v[58:59], v[58:59], 0, s[4:5]
	v_lshlrev_b32_e32 v130, 1, v132
	v_lshl_add_u64 v[58:59], v[58:59], 0, v[130:131]
	global_store_dwordx2 v[58:59], v[56:57], off
	v_mul_f32_e32 v56, v124, v163
	v_mul_f32_e32 v20, v20, v56
	v_mul_f32_e32 v56, v125, v163
	v_mul_f32_e32 v21, v21, v56
	v_cvt_pk_bf16_f32 v20, v20, v21
	v_mul_f32_e32 v21, v126, v163
	v_mul_f32_e32 v21, v22, v21
	v_mul_f32_e32 v22, v127, v163
	v_mul_f32_e32 v22, v23, v22
	v_cvt_pk_bf16_f32 v21, v21, v22
	global_store_dwordx2 v[58:59], v[20:21], off offset:16
	v_mul_f32_e32 v20, v135, v163
	v_mul_f32_e32 v21, v148, v163
	v_mul_f32_e32 v22, v150, v163
	v_mul_f32_e32 v20, v60, v20
	v_mul_f32_e32 v21, v61, v21
	v_cvt_pk_bf16_f32 v20, v20, v21
	v_mul_f32_e32 v21, v149, v163
	v_mul_f32_e32 v21, v62, v21
	v_mul_f32_e32 v22, v63, v22
	v_cvt_pk_bf16_f32 v21, v21, v22
	global_store_dwordx2 v[58:59], v[20:21], off offset:32
	v_mul_f32_e32 v20, v151, v163
	v_mul_f32_e32 v21, v152, v163
	v_mul_f32_e32 v20, v24, v20
	v_mul_f32_e32 v21, v25, v21
	v_cvt_pk_bf16_f32 v20, v20, v21
	v_mul_f32_e32 v21, v153, v163
	v_mul_f32_e32 v21, v26, v21
	v_mul_f32_e32 v22, v154, v163
	v_mul_f32_e32 v22, v27, v22
	v_cvt_pk_bf16_f32 v21, v21, v22
	global_store_dwordx2 v[58:59], v[20:21], off offset:48
	v_mul_f32_e32 v20, v155, v163
	v_mul_f32_e32 v21, v156, v163
	v_mul_f32_e32 v20, v28, v20
	v_mul_f32_e32 v21, v29, v21
	v_cvt_pk_bf16_f32 v20, v20, v21
	v_mul_f32_e32 v21, v157, v163
	v_mul_f32_e32 v21, v30, v21
	v_mul_f32_e32 v22, v158, v163
	v_mul_f32_e32 v22, v31, v22
	v_cvt_pk_bf16_f32 v21, v21, v22
	global_store_dwordx2 v[58:59], v[20:21], off offset:64
	v_mul_f32_e32 v20, v159, v163
	v_mul_f32_e32 v21, v160, v163
	v_mul_f32_e32 v20, v64, v20
	v_mul_f32_e32 v21, v65, v21
	v_cvt_pk_bf16_f32 v20, v20, v21
	v_mul_f32_e32 v21, v161, v163
	v_mul_f32_e32 v21, v66, v21
	v_mul_f32_e32 v22, v162, v163
	v_mul_f32_e32 v22, v67, v22
	v_cvt_pk_bf16_f32 v21, v21, v22
	global_store_dwordx2 v[58:59], v[20:21], off offset:80
	v_mul_f32_e32 v20, v55, v163
	v_mul_f32_e32 v21, v53, v163
	v_mul_f32_e32 v20, v68, v20
	v_mul_f32_e32 v21, v69, v21
	v_cvt_pk_bf16_f32 v20, v20, v21
	v_mul_f32_e32 v21, v51, v163
	v_mul_f32_e32 v21, v70, v21
	v_mul_f32_e32 v22, v49, v163
	v_mul_f32_e32 v22, v71, v22
	v_cvt_pk_bf16_f32 v21, v21, v22
	global_store_dwordx2 v[58:59], v[20:21], off offset:96
	v_mul_f32_e32 v20, v54, v163
	v_mul_f32_e32 v21, v52, v163
	v_mul_f32_e32 v20, v72, v20
	v_mul_f32_e32 v21, v73, v21
	v_cvt_pk_bf16_f32 v20, v20, v21
	v_mul_f32_e32 v21, v50, v163
	v_mul_f32_e32 v21, v74, v21
	v_mul_f32_e32 v22, v48, v163
	v_mul_f32_e32 v22, v75, v22
	v_cvt_pk_bf16_f32 v21, v21, v22
	global_store_dwordx2 v[58:59], v[20:21], off offset:112
	v_mul_f32_e32 v20, v39, v163
	v_mul_f32_e32 v21, v37, v163
	v_mul_f32_e32 v20, v76, v20
	v_mul_f32_e32 v21, v21, v77
	v_cvt_pk_bf16_f32 v20, v20, v21
	v_mul_f32_e32 v21, v35, v163
	v_mul_f32_e32 v21, v21, v78
	v_mul_f32_e32 v22, v33, v163
	v_mul_f32_e32 v22, v22, v79
	v_cvt_pk_bf16_f32 v21, v21, v22
	global_store_dwordx2 v[58:59], v[20:21], off offset:128
	v_mul_f32_e32 v20, v38, v163
	v_mul_f32_e32 v21, v36, v163
	v_mul_f32_e32 v20, v20, v80
	v_mul_f32_e32 v21, v21, v81
	v_cvt_pk_bf16_f32 v20, v20, v21
	v_mul_f32_e32 v21, v34, v163
	v_mul_f32_e32 v21, v21, v82
	v_mul_f32_e32 v22, v32, v163
	v_mul_f32_e32 v22, v22, v83
	v_cvt_pk_bf16_f32 v21, v21, v22
	global_store_dwordx2 v[58:59], v[20:21], off offset:144
	v_mul_f32_e32 v20, v47, v163
	v_mul_f32_e32 v21, v45, v163
	v_mul_f32_e32 v20, v20, v84
	v_mul_f32_e32 v21, v21, v85
	v_cvt_pk_bf16_f32 v20, v20, v21
	v_mul_f32_e32 v21, v43, v163
	v_mul_f32_e32 v21, v21, v86
	v_mul_f32_e32 v22, v41, v163
	v_mul_f32_e32 v22, v22, v87
	v_cvt_pk_bf16_f32 v21, v21, v22
	global_store_dwordx2 v[58:59], v[20:21], off offset:160
	v_mul_f32_e32 v20, v46, v163
	v_mul_f32_e32 v21, v44, v163
	v_mul_f32_e32 v20, v20, v88
	v_mul_f32_e32 v21, v21, v89
	v_cvt_pk_bf16_f32 v20, v20, v21
	v_mul_f32_e32 v21, v42, v163
	v_mul_f32_e32 v21, v21, v90
	v_mul_f32_e32 v22, v40, v163
	v_mul_f32_e32 v22, v22, v91
	v_cvt_pk_bf16_f32 v21, v21, v22
	global_store_dwordx2 v[58:59], v[20:21], off offset:176
	v_mul_f32_e32 v20, v109, v163
	v_mul_f32_e32 v21, v111, v163
	v_mul_f32_e32 v20, v20, v92
	v_mul_f32_e32 v21, v21, v93
	v_mul_f32_e32 v17, v17, v95
	v_cvt_pk_bf16_f32 v20, v20, v21
	v_mul_f32_e32 v19, v19, v94
	v_cvt_pk_bf16_f32 v21, v19, v17
	v_mul_f32_e32 v17, v108, v163
	v_mul_f32_e32 v17, v17, v96
	v_mul_f32_e32 v19, v110, v163
	global_store_dwordx2 v[58:59], v[20:21], off offset:192
	v_mul_f32_e32 v19, v19, v97
	v_cvt_pk_bf16_f32 v20, v17, v19
	v_mul_f32_e32 v17, v18, v163
	v_mul_f32_e32 v17, v17, v98
	v_mul_f32_e32 v16, v16, v99
	v_cvt_pk_bf16_f32 v21, v17, v16
	v_mul_f32_e32 v16, v113, v163
	v_mul_f32_e32 v17, v115, v163
	v_mul_f32_e32 v16, v16, v100
	v_mul_f32_e32 v17, v17, v101
	global_store_dwordx2 v[58:59], v[20:21], off offset:208
	v_cvt_pk_bf16_f32 v16, v16, v17
	v_mul_f32_e32 v17, v117, v163
	v_mul_f32_e32 v17, v17, v102
	v_mul_f32_e32 v18, v119, v163
	v_mul_f32_e32 v18, v18, v103
	v_cvt_pk_bf16_f32 v17, v17, v18
	global_store_dwordx2 v[58:59], v[16:17], off offset:224
	v_mul_f32_e32 v16, v112, v163
	v_mul_f32_e32 v17, v114, v163
	v_mul_f32_e32 v16, v16, v104
	v_mul_f32_e32 v17, v17, v105
	v_cvt_pk_bf16_f32 v16, v16, v17
	v_mul_f32_e32 v17, v116, v163
	v_mul_f32_e32 v17, v17, v106
	v_mul_f32_e32 v18, v118, v163
	v_mul_f32_e32 v18, v18, v107
	v_cvt_pk_bf16_f32 v17, v17, v18
	global_store_dwordx2 v[58:59], v[16:17], off offset:240
	s_load_dword s54, s[6:7], 0x0
	s_waitcnt lgkmcnt(0)
	s_add_i32 s46, s54, s46
	s_cmpk_gt_i32 s46, 0x1ff
	s_cbranch_scc1 .LBB0_1463
.LBB0_1447:
	s_lshl_b32 s4, s46, 5
	s_and_b32 s14, s46, 0x3fffff00
	s_and_b32 s4, s4, 0xe0
	s_bfe_u32 s15, s46, 0x50003
	s_or_b32 s4, s14, s4
	s_or_b32 s4, s4, s15
	s_lshl_b32 s4, s4, 2
	s_add_i32 s18, s4, s36
	s_lshr_b32 s4, s18, 5
	s_and_b32 s48, s4, 14
	s_ashr_i32 s14, s18, 9
	s_bfe_u32 s16, s18, 0x30006
	s_lshl_b32 s47, s48, 6
	s_ashr_i32 s15, s14, 31
	s_mul_i32 s34, s16, 0x440000
	s_add_u32 s16, s28, s34
	s_addc_u32 s17, s29, 0
	s_lshl_b32 s18, s18, 6
	s_mul_i32 s22, s14, 0x1100
	s_and_b32 s18, s18, 0xf80
	s_mul_hi_i32 s19, s14, 0x1100
	v_or_b32_e32 v130, s18, v170
	s_add_u32 s18, s22, 0x100
	s_addc_u32 s19, s19, 0
	v_lshl_add_u64 v[16:17], s[18:19], 0, v[130:131]
	v_mov_b64_e32 v[18:19], s[30:31]
	v_mad_u64_u32 v[150:151], s[18:19], v16, s37, v[18:19]
	v_mad_i32_i24 v151, v17, s37, v151
	s_lshl_b32 s18, s48, 7
	s_mov_b32 s19, s5
	v_lshl_add_u64 v[16:17], v[150:151], 0, s[18:19]
	v_mov_b32_e32 v135, v131
	s_mul_i32 s22, s14, 0x44
	s_mul_i32 s4, s48, 0x220000
	v_lshl_add_u64 v[16:17], v[16:17], 0, v[134:135]
	s_ashr_i32 s23, s22, 31
	global_load_dwordx4 v[112:115], v[16:17], off
	global_load_dwordx4 v[116:119], v[16:17], off offset:32
	global_load_dwordx4 v[120:123], v[16:17], off offset:64
	global_load_dwordx4 v[124:127], v[16:17], off offset:96
	v_lshl_add_u64 v[16:17], v[140:141], 0, s[4:5]
	v_lshl_add_u64 v[18:19], s[16:17], 0, v[138:139]
	s_lshl_b64 s[16:17], s[22:23], 13
	v_readfirstlane_b32 s4, v182
	v_add_u32_e32 v209, 0x4000, v182
	v_lshl_add_u64 v[18:19], v[18:19], 0, s[8:9]
	v_lshl_add_u64 v[20:21], v[16:17], 0, s[16:17]
	s_lshl_b64 s[24:25], s[22:23], 14
	s_mov_b32 m0, s4
	v_readfirstlane_b32 s4, v209
	v_add_u32_e32 v211, 0x6000, v182
	s_or_b32 s26, s22, 1
	s_barrier
	v_lshl_add_u64 v[152:153], v[18:19], 0, s[24:25]
	global_load_lds_dwordx4 v[20:21], off
	s_mov_b32 m0, s4
	v_readfirstlane_b32 s4, v211
	s_ashr_i32 s27, s26, 31
	v_add_u32_e32 v213, 0x8000, v182
	global_load_lds_dwordx4 v[152:153], off
	v_lshl_add_u64 v[154:155], v[152:153], 0, s[10:11]
	s_mov_b32 m0, s4
	s_lshl_b64 s[18:19], s[26:27], 13
	s_lshl_b64 s[26:27], s[26:27], 14
	v_readfirstlane_b32 s4, v213
	v_add_u32_e32 v215, 0xc000, v182
	global_load_lds_dwordx4 v[154:155], off
	v_lshl_add_u64 v[20:21], v[16:17], 0, s[18:19]
	v_lshl_add_u64 v[156:157], v[18:19], 0, s[26:27]
	s_mov_b32 m0, s4
	v_readfirstlane_b32 s4, v215
	v_add_u32_e32 v217, 0xe000, v182
	s_or_b32 s26, s22, 2
	global_load_lds_dwordx4 v[20:21], off
	s_mov_b32 m0, s4
	v_readfirstlane_b32 s4, v217
	s_ashr_i32 s27, s26, 31
	v_add_u32_e32 v218, s42, v181
	global_load_lds_dwordx4 v[156:157], off
	v_lshl_add_u64 v[158:159], v[156:157], 0, s[10:11]
	s_mov_b32 m0, s4
	s_lshl_b64 s[22:23], s[26:27], 13
	v_readfirstlane_b32 s4, v218
	v_add_u32_e32 v219, s43, v181
	global_load_lds_dwordx4 v[158:159], off
	v_lshl_add_u64 v[16:17], v[16:17], 0, s[22:23]
	s_lshl_b64 s[26:27], s[26:27], 14
	s_mov_b32 m0, s4
	v_readfirstlane_b32 s4, v219
	v_add_u32_e32 v220, s44, v181
	v_lshl_add_u64 v[160:161], v[18:19], 0, s[26:27]
	global_load_lds_dwordx4 v[16:17], off
	s_mov_b32 m0, s4
	v_readfirstlane_b32 s4, v220
	global_load_lds_dwordx4 v[160:161], off
	v_lshl_add_u64 v[162:163], v[160:161], 0, s[10:11]
	s_mov_b32 m0, s4
	s_add_u32 s24, s34, s24
	global_load_lds_dwordx4 v[162:163], off
	s_addc_u32 s25, 0, s25
	s_waitcnt vmcnt(6)
	v_lshl_add_u64 v[148:149], v[142:143], 0, s[24:25]
	s_add_u32 s24, s34, s16
	s_addc_u32 s25, 0, s17
	v_lshl_add_u64 v[164:165], v[144:145], 0, s[24:25]
	s_mov_b32 s4, 0
	s_mov_b32 s49, 0x18000
	v_mov_b64_e32 v[166:167], v[148:149]
	v_mov_b32_e32 v64, v131
	v_mov_b32_e32 v65, v131
	v_mov_b32_e32 v66, v131
	v_mov_b32_e32 v67, v131
	v_mov_b32_e32 v68, v131
	v_mov_b32_e32 v69, v131
	v_mov_b32_e32 v70, v131
	v_mov_b32_e32 v71, v131
	v_mov_b32_e32 v72, v131
	v_mov_b32_e32 v73, v131
	v_mov_b32_e32 v74, v131
	v_mov_b32_e32 v75, v131
	v_mov_b32_e32 v76, v131
	v_mov_b32_e32 v77, v131
	v_mov_b32_e32 v78, v131
	v_mov_b32_e32 v79, v131
	v_mov_b32_e32 v48, v131
	v_mov_b32_e32 v49, v131
	v_mov_b32_e32 v50, v131
	v_mov_b32_e32 v51, v131
	v_mov_b32_e32 v52, v131
	v_mov_b32_e32 v53, v131
	v_mov_b32_e32 v54, v131
	v_mov_b32_e32 v55, v131
	v_mov_b32_e32 v56, v131
	v_mov_b32_e32 v57, v131
	v_mov_b32_e32 v58, v131
	v_mov_b32_e32 v59, v131
	v_mov_b32_e32 v60, v131
	v_mov_b32_e32 v61, v131
	v_mov_b32_e32 v62, v131
	v_mov_b32_e32 v63, v131
	v_mov_b32_e32 v32, v131
	v_mov_b32_e32 v33, v131
	v_mov_b32_e32 v34, v131
	v_mov_b32_e32 v35, v131
	v_mov_b32_e32 v36, v131
	v_mov_b32_e32 v37, v131
	v_mov_b32_e32 v38, v131
	v_mov_b32_e32 v39, v131
	v_mov_b32_e32 v40, v131
	v_mov_b32_e32 v41, v131
	v_mov_b32_e32 v42, v131
	v_mov_b32_e32 v43, v131
	v_mov_b32_e32 v44, v131
	v_mov_b32_e32 v45, v131
	v_mov_b32_e32 v46, v131
	v_mov_b32_e32 v47, v131
	v_mov_b32_e32 v16, v131
	v_mov_b32_e32 v17, v131
	v_mov_b32_e32 v18, v131
	v_mov_b32_e32 v19, v131
	v_mov_b32_e32 v20, v131
	v_mov_b32_e32 v21, v131
	v_mov_b32_e32 v22, v131
	v_mov_b32_e32 v23, v131
	v_mov_b32_e32 v24, v131
	v_mov_b32_e32 v25, v131
	v_mov_b32_e32 v26, v131
	v_mov_b32_e32 v27, v131
	v_mov_b32_e32 v28, v131
	v_mov_b32_e32 v29, v131
	v_mov_b32_e32 v30, v131
	v_mov_b32_e32 v31, v131
	s_barrier
	s_waitcnt vmcnt(0)
	s_mov_b32 s90, 0
	s_mov_b32 s88, 0
	s_mov_b32 s89, 0
	s_lshr_b32 s91, s2, 7
	s_lshl_b32 s92, s98, 1
	s_add_i32 s91, s91, s92
	s_mul_i32 s92, s91, 0xab
	s_lshr_b32 s92, s92, 9
	s_mul_i32 s93, s92, 3
	s_sub_i32 s91, s91, s93
	v_mbcnt_lo_u32_b32 v222, -1, 0
	v_mbcnt_hi_u32_b32 v222, -1, v222
	s_and_b32 s93, s2, 0x7f
	s_lshl_b32 s93, s93, 9
	s_or_b32 s93, s93, s63
	v_or_b32_e32 v222, s93, v222
	s_cmp_eq_u32 s91, 2
	s_cselect_b32 s93, 12, 11
	v_lshrrev_b32_e32 v223, s93, v222
	v_and_b32_e32 v208, 7, v222
	v_lshl_or_b32 v223, v223, 3, v208
	s_cselect_b32 s93, 6, 5
	v_bfe_u32 v208, v222, 6, s93
	v_lshrrev_b32_e32 v222, 1, v222
	v_and_b32_e32 v222, 28, v222
	v_lshl_or_b32 v222, v208, 5, v222
	v_lshlrev_b32_e32 v222, 2, v222
	s_cselect_b32 s93, 16, 15
	v_lshlrev_b32_e32 v223, s93, v223
	v_add_u32_e32 v222, v223, v222
	s_cselect_b32 s94, 1, 0
	s_lshl_b32 s94, 0x1000, s94
	s_lshl_b32 s92, s92, 23
	s_cmp_eq_u32 s91, 0
	s_cselect_b64 s[100:101], s[76:77], s[78:79]
	s_cmp_eq_u32 s91, 2
	s_cselect_b64 s[100:101], s[80:81], s[100:101]
	s_add_u32 s100, s100, s92
	s_addc_u32 s101, s101, 0
	s_mov_b32 s95, 1
	s_branch .LBB0_1449
.LBB0_1448:
	s_cmp_lt_u32 s4, 64
	s_cbranch_scc0 .Lcj_cx_0
	s_and_b32 s93, s4, 7
	s_cmp_eq_u32 s93, 5
	s_cbranch_scc1 .Lcj_c5_0
	s_cmp_eq_u32 s93, 7
	s_cbranch_scc1 .Lcj_c7_0
.Lcj_cx_0:
	v_add_f32_e32 v96, v135, v96
	v_add_f32_e32 v96, v97, v96
	v_add_f32_e32 v96, v98, v96
	v_add_f32_e32 v96, v99, v96
	v_add_f32_e32 v96, v100, v96
	v_add_f32_e32 v96, v101, v96
	v_add_f32_e32 v96, v102, v96
	v_add_f32_e32 v96, v103, v96
	v_add_f32_e32 v96, v104, v96
	v_add_f32_e32 v96, v105, v96
	v_add_f32_e32 v96, v106, v96
	v_add_f32_e32 v96, v107, v96
	v_add_f32_e32 v96, v108, v96
	v_add_f32_e32 v96, v109, v96
	v_add_f32_e32 v96, v110, v96
	v_add_f32_e32 v96, v111, v96
	v_add_f32_e32 v80, v80, v96
	v_add_f32_e32 v80, v81, v80
	v_add_f32_e32 v80, v82, v80
	v_add_f32_e32 v80, v83, v80
	v_add_f32_e32 v80, v84, v80
	v_add_f32_e32 v80, v85, v80
	v_add_f32_e32 v80, v86, v80
	v_add_f32_e32 v80, v87, v80
	v_add_f32_e32 v80, v88, v80
	v_add_f32_e32 v80, v89, v80
	v_add_f32_e32 v80, v90, v80
	v_add_f32_e32 v80, v91, v80
	v_add_f32_e32 v80, v92, v80
	v_add_f32_e32 v80, v93, v80
	v_add_f32_e32 v80, v94, v80
	v_add_f32_e32 v135, v95, v80
	s_branch .Lcj_common_0
.Lcj_c5_0:
	v_add_f32_e32 v96, v135, v96
	s_waitcnt vmcnt(6)
	v_cvt_pk_bf16_f32 v224, v224, v228
	v_add_f32_e32 v96, v97, v96
	v_cvt_pk_bf16_f32 v228, v225, v229
	v_cvt_pk_bf16_f32 v225, v232, v236
	v_add_f32_e32 v96, v98, v96
	v_cvt_pk_bf16_f32 v232, v226, v230
	v_cvt_pk_bf16_f32 v226, v240, v244
	v_add_f32_e32 v96, v99, v96
	v_cvt_pk_bf16_f32 v236, v227, v231
	v_cvt_pk_bf16_f32 v227, v248, v252
	v_add_f32_e32 v96, v100, v96
	v_cvt_pk_bf16_f32 v229, v233, v237
	v_cvt_pk_bf16_f32 v230, v241, v245
	v_add_f32_e32 v96, v101, v96
	v_cvt_pk_bf16_f32 v231, v249, v253
	v_cvt_pk_bf16_f32 v233, v234, v238
	v_add_f32_e32 v96, v102, v96
	v_cvt_pk_bf16_f32 v234, v242, v246
	v_cvt_pk_bf16_f32 v237, v235, v239
	v_add_f32_e32 v96, v103, v96
	v_cvt_pk_bf16_f32 v235, v250, v254
	v_cvt_pk_bf16_f32 v238, v243, v247
	v_add_f32_e32 v96, v104, v96
	v_cvt_pk_bf16_f32 v239, v251, v255
	s_lshr_b32 s91, s2, 7
	v_add_f32_e32 v96, v105, v96
	s_lshl_b32 s92, s98, 1
	s_add_i32 s91, s91, s92
	v_add_f32_e32 v96, v106, v96
	s_mul_i32 s92, s91, 0xab
	s_lshr_b32 s92, s92, 9
	v_add_f32_e32 v96, v107, v96
	s_mul_i32 s93, s92, 3
	s_sub_i32 s91, s91, s93
	v_add_f32_e32 v96, v108, v96
	v_mbcnt_lo_u32_b32 v222, -1, 0
	v_mbcnt_hi_u32_b32 v222, -1, v222
	v_add_f32_e32 v96, v109, v96
	s_and_b32 s93, s2, 0x7f
	s_lshl_b32 s93, s93, 9
	v_add_f32_e32 v96, v110, v96
	s_or_b32 s93, s93, s63
	v_or_b32_e32 v222, s93, v222
	v_add_f32_e32 v96, v111, v96
	s_cmp_eq_u32 s91, 2
	s_cselect_b32 s93, 12, 11
	v_add_f32_e32 v80, v80, v96
	v_lshrrev_b32_e32 v223, s93, v222
	v_and_b32_e32 v208, 7, v222
	v_add_f32_e32 v80, v81, v80
	v_lshl_or_b32 v223, v223, 3, v208
	s_cselect_b32 s93, 6, 5
	v_add_f32_e32 v80, v82, v80
	v_bfe_u32 v208, v222, 6, s93
	v_lshrrev_b32_e32 v222, 1, v222
	v_add_f32_e32 v80, v83, v80
	v_and_b32_e32 v222, 28, v222
	v_lshl_or_b32 v222, v208, 5, v222
	v_add_f32_e32 v80, v84, v80
	s_cselect_b64 vcc, exec, 0
	s_cselect_b32 s94, 11, 12
	v_add_f32_e32 v80, v85, v80
	s_cselect_b64 s[100:101], s[86:87], s[84:85]
	s_cselect_b32 s93, 22, 23
	v_add_f32_e32 v80, v86, v80
	v_lshrrev_b32_e32 v208, 7, v222
	v_and_b32_e32 v240, 0x7f, v222
	v_add_f32_e32 v80, v87, v80
	s_lshl_b32 s92, s92, s93
	v_lshl_or_b32 v208, v208, 8, v240
	v_add_f32_e32 v80, v88, v80
	s_lshl_b32 s93, s91, 7
	v_or_b32_e32 v208, s93, v208
	v_add_f32_e32 v80, v89, v80
	v_cndmask_b32_e32 v222, v208, v222, vcc
	v_lshlrev_b32_e32 v222, s94, v222
	v_add_f32_e32 v80, v90, v80
	s_lshl_b32 s94, 1, s94
	v_lshl_or_b32 v222, v223, 4, v222
	v_add_f32_e32 v80, v91, v80
	s_add_u32 s100, s100, s92
	s_addc_u32 s101, s101, 0
	v_add_f32_e32 v80, v92, v80
	s_mov_b32 s95, 5
	v_add_f32_e32 v80, v93, v80
	v_add_f32_e32 v80, v94, v80
	v_add_f32_e32 v135, v95, v80
	s_branch .Lcj_common_0
.Lcj_c7_0:
	v_add_f32_e32 v96, v135, v96
	s_add_i32 s98, s98, 1
	s_min_u32 s98, s98, 47
	v_add_f32_e32 v96, v97, v96
	s_lshr_b32 s91, s2, 7
	s_lshl_b32 s92, s98, 1
	v_add_f32_e32 v96, v98, v96
	s_add_i32 s91, s91, s92
	s_mul_i32 s92, s91, 0xab
	v_add_f32_e32 v96, v99, v96
	s_lshr_b32 s92, s92, 9
	s_mul_i32 s93, s92, 3
	v_add_f32_e32 v96, v100, v96
	s_sub_i32 s91, s91, s93
	v_mbcnt_lo_u32_b32 v222, -1, 0
	v_add_f32_e32 v96, v101, v96
	v_mbcnt_hi_u32_b32 v222, -1, v222
	s_and_b32 s93, s2, 0x7f
	v_add_f32_e32 v96, v102, v96
	s_lshl_b32 s93, s93, 9
	s_or_b32 s93, s93, s63
	v_add_f32_e32 v96, v103, v96
	v_or_b32_e32 v222, s93, v222
	s_cmp_eq_u32 s91, 2
	v_add_f32_e32 v96, v104, v96
	s_cselect_b32 s93, 12, 11
	v_lshrrev_b32_e32 v223, s93, v222
	v_add_f32_e32 v96, v105, v96
	v_and_b32_e32 v208, 7, v222
	v_lshl_or_b32 v223, v223, 3, v208
	v_add_f32_e32 v96, v106, v96
	s_cselect_b32 s93, 6, 5
	v_bfe_u32 v208, v222, 6, s93
	v_add_f32_e32 v96, v107, v96
	v_lshrrev_b32_e32 v222, 1, v222
	v_and_b32_e32 v222, 28, v222
	v_add_f32_e32 v96, v108, v96
	v_lshl_or_b32 v222, v208, 5, v222
	v_lshlrev_b32_e32 v222, 2, v222
	v_add_f32_e32 v96, v109, v96
	s_cselect_b32 s93, 16, 15
	v_lshlrev_b32_e32 v223, s93, v223
	v_add_f32_e32 v96, v110, v96
	v_add_u32_e32 v222, v223, v222
	s_cselect_b32 s94, 1, 0
	v_add_f32_e32 v96, v111, v96
	s_lshl_b32 s94, 0x1000, s94
	s_lshl_b32 s92, s92, 23
	v_add_f32_e32 v80, v80, v96
	s_cmp_eq_u32 s91, 0
	s_cselect_b64 s[100:101], s[76:77], s[78:79]
	v_add_f32_e32 v80, v81, v80
	s_cmp_eq_u32 s91, 2
	s_cselect_b64 s[100:101], s[80:81], s[100:101]
	v_add_f32_e32 v80, v82, v80
	s_add_u32 s100, s100, s92
	s_addc_u32 s101, s101, 0
	v_add_f32_e32 v80, v83, v80
	s_mov_b32 s95, 1
	s_cmp_lt_u32 s4, 56
	v_add_f32_e32 v80, v84, v80
	s_cselect_b32 s95, 1, 0
	v_add_f32_e32 v80, v85, v80
	v_add_f32_e32 v80, v86, v80
	v_add_f32_e32 v80, v87, v80
	v_add_f32_e32 v80, v88, v80
	v_add_f32_e32 v80, v89, v80
	v_add_f32_e32 v80, v90, v80
	v_add_f32_e32 v80, v91, v80
	v_add_f32_e32 v80, v92, v80
	v_add_f32_e32 v80, v93, v80
	v_add_f32_e32 v80, v94, v80
	v_add_f32_e32 v135, v95, v80
.Lcj_common_0:
	s_waitcnt lgkmcnt(0)
	s_mov_b32 s89, s88
	s_mov_b32 s88, s90
	s_mov_b32 s90, 0
	s_add_i32 s4, s4, 1
	s_add_i32 s49, s49, 0x8000
	v_lshl_add_u64 v[166:167], v[166:167], 0, s[12:13]
	v_lshl_add_u64 v[164:165], v[164:165], 0, s[10:11]
	s_cmp_eq_u32 s49, 0x238000
	s_barrier
	s_cbranch_scc1 .LBB0_1455
.LBB0_1449:
	s_cmp_gt_u32 s4, 64
	s_cselect_b64 s[26:27], -1, 0
	s_and_b64 vcc, exec, s[26:27]
	s_cbranch_vccnz .LBB0_1451
	s_and_b32 s34, s49, 0x18000
	v_add_u32_e32 v82, s34, v182
	v_add_u32_e32 v80, 0x4000, v82
	v_readfirstlane_b32 s34, v82
	s_mov_b32 m0, s34
	v_readfirstlane_b32 s34, v80
	v_add_u32_e32 v82, 0x6000, v82
	global_load_lds_dwordx4 v[164:165], off
	s_mov_b32 m0, s34
	v_readfirstlane_b32 s34, v82
	global_load_lds_dwordx4 v[166:167], off
	v_lshl_add_u64 v[80:81], v[166:167], 0, s[10:11]
	s_mov_b32 m0, s34
	s_nop 0
	global_load_lds_dwordx4 v[80:81], off
.LBB0_1451:
	s_cmp_eq_u32 s95, 0
	s_cbranch_scc1 .Lcjh_done_0
	s_cmp_eq_u32 s95, 1
	s_cbranch_scc0 .Lcjh_n1_0
	global_load_dwordx4 v[224:227], v222, s[100:101] nt
	v_add_u32_e32 v222, s94, v222
	global_load_dwordx4 v[228:231], v222, s[100:101] nt
	v_add_u32_e32 v222, s94, v222
	s_mov_b32 s90, 2
	s_add_i32 s95, s95, 1
	s_branch .Lcjh_done_0
.Lcjh_n1_0:
	s_cmp_eq_u32 s95, 2
	s_cbranch_scc0 .Lcjh_n2_0
	global_load_dwordx4 v[232:235], v222, s[100:101] nt
	v_add_u32_e32 v222, s94, v222
	global_load_dwordx4 v[236:239], v222, s[100:101] nt
	v_add_u32_e32 v222, s94, v222
	s_mov_b32 s90, 2
	s_add_i32 s95, s95, 1
	s_branch .Lcjh_done_0
.Lcjh_n2_0:
	s_cmp_eq_u32 s95, 3
	s_cbranch_scc0 .Lcjh_n3_0
	global_load_dwordx4 v[240:243], v222, s[100:101] nt
	v_add_u32_e32 v222, s94, v222
	global_load_dwordx4 v[244:247], v222, s[100:101] nt
	v_add_u32_e32 v222, s94, v222
	s_mov_b32 s90, 2
	s_add_i32 s95, s95, 1
	s_branch .Lcjh_done_0
.Lcjh_n3_0:
	s_cmp_eq_u32 s95, 4
	s_cbranch_scc0 .Lcjh_n4_0
	global_load_dwordx4 v[248:251], v222, s[100:101] nt
	v_add_u32_e32 v222, s94, v222
	global_load_dwordx4 v[252:255], v222, s[100:101] nt
	v_add_u32_e32 v222, s94, v222
	s_mov_b32 s90, 2
	s_mov_b32 s95, 0
	s_branch .Lcjh_done_0
.Lcjh_n4_0:
	s_cmp_eq_u32 s95, 5
	s_cbranch_scc0 .Lcjh_n5_0
	global_store_dwordx4 v222, v[224:227], s[100:101]
	v_add_u32_e32 v222, s94, v222
	global_store_dwordx4 v222, v[228:231], s[100:101]
	v_add_u32_e32 v222, s94, v222
	s_mov_b32 s90, 2
	s_mov_b32 s95, 6
	s_branch .Lcjh_done_0
.Lcjh_n5_0:
	global_store_dwordx4 v222, v[232:235], s[100:101]
	v_add_u32_e32 v222, s94, v222
	global_store_dwordx4 v222, v[236:239], s[100:101]
	v_add_u32_e32 v222, s94, v222
	s_mov_b32 s90, 2
	s_mov_b32 s95, 0
.Lcjh_done_0:
	s_add_i32 s34, s49, 0xfffe8000
	s_and_b32 s34, s34, 0x18000
	s_add_i32 s34, s34, 0
	v_add3_u32 v84, s34, v177, v176
	ds_read_b128 v[80:83], v84
	ds_read_b128 v[184:187], v84 offset:512
	v_add3_u32 v85, s34, v178, v176
	v_add3_u32 v84, s34, v179, v176
	v_add_u32_e32 v200, s34, v168
	v_add_u32_e32 v201, s34, v169
	s_and_b64 vcc, exec, s[26:27]
	s_waitcnt lgkmcnt(0)
	v_mfma_f32_32x32x16_bf16 v[96:111], v[80:83], v[112:115], v[0:15]
	ds_read_b128 v[80:83], v85 offset:2048
	ds_read_b128 v[188:191], v85 offset:2560
	v_add3_u32 v85, s34, v180, v176
	s_mov_b64 s[34:35], -1
	ds_read_b128 v[192:195], v84 offset:4608
	s_waitcnt lgkmcnt(0)
	v_mfma_f32_32x32x16_bf16 v[96:111], v[80:83], v[116:119], v[96:111]
	ds_read_b128 v[80:83], v84 offset:4096
	s_waitcnt lgkmcnt(0)
	v_mfma_f32_32x32x16_bf16 v[96:111], v[80:83], v[120:123], v[96:111]
	ds_read_b128 v[80:83], v85 offset:6144
	ds_read_b128 v[196:199], v85 offset:6656
	s_waitcnt lgkmcnt(0)
	v_mfma_f32_32x32x16_bf16 v[96:111], v[80:83], v[124:127], v[96:111]
	v_mfma_f32_32x32x16_bf16 v[80:95], v[184:187], v[112:115], v[0:15]
	ds_read_b128 v[184:187], v200 offset:16384
	s_nop 9
	v_exp_f32_e32 v96, v96
	v_exp_f32_e32 v97, v97
	v_exp_f32_e32 v98, v98
	v_exp_f32_e32 v99, v99
	v_exp_f32_e32 v100, v100
	v_exp_f32_e32 v101, v101
	v_mfma_f32_32x32x16_bf16 v[80:95], v[188:191], v[116:119], v[80:95]
	v_exp_f32_e32 v102, v102
	v_exp_f32_e32 v103, v103
	v_cvt_pk_bf16_f32 v188, v96, v97
	v_cvt_pk_bf16_f32 v189, v98, v99
	v_cvt_pk_bf16_f32 v190, v100, v101
	v_cvt_pk_bf16_f32 v191, v102, v103
	v_exp_f32_e32 v104, v104
	v_mfma_f32_32x32x16_bf16 v[80:95], v[192:195], v[120:123], v[80:95]
	ds_read_b128 v[192:195], v200 offset:17408
	v_exp_f32_e32 v105, v105
	v_exp_f32_e32 v106, v106
	v_exp_f32_e32 v107, v107
	v_exp_f32_e32 v108, v108
	v_exp_f32_e32 v109, v109
	v_exp_f32_e32 v110, v110
	v_mfma_f32_32x32x16_bf16 v[80:95], v[196:199], v[124:127], v[80:95]
	v_exp_f32_e32 v111, v111
	s_waitcnt lgkmcnt(0)
	v_mfma_f32_32x32x16_bf16 v[64:79], v[184:187], v[188:191], v[64:79]
	ds_read_b128 v[184:187], v201 offset:16896
	ds_read_b128 v[196:199], v201 offset:17920
	s_nop 6
	v_exp_f32_e32 v80, v80
	v_exp_f32_e32 v81, v81
	v_exp_f32_e32 v82, v82
	v_exp_f32_e32 v83, v83
	v_exp_f32_e32 v84, v84
	v_exp_f32_e32 v85, v85
	s_waitcnt lgkmcnt(0)
	v_mfma_f32_32x32x16_bf16 v[48:63], v[184:187], v[188:191], v[48:63]
	ds_read_b128 v[184:187], v200 offset:20480
	v_exp_f32_e32 v86, v86
	v_exp_f32_e32 v87, v87
	v_exp_f32_e32 v88, v88
	v_exp_f32_e32 v89, v89
	v_exp_f32_e32 v90, v90
	v_exp_f32_e32 v91, v91
	v_mfma_f32_32x32x16_bf16 v[32:47], v[192:195], v[188:191], v[32:47]
	ds_read_b128 v[192:195], v200 offset:21504
	v_exp_f32_e32 v92, v92
	v_exp_f32_e32 v93, v93
	v_exp_f32_e32 v94, v94
	v_exp_f32_e32 v95, v95
	v_mfma_f32_32x32x16_bf16 v[16:31], v[196:199], v[188:191], v[16:31]
	v_cvt_pk_bf16_f32 v188, v104, v105
	v_cvt_pk_bf16_f32 v189, v106, v107
	v_cvt_pk_bf16_f32 v190, v108, v109
	v_cvt_pk_bf16_f32 v191, v110, v111
	s_waitcnt lgkmcnt(0)
	s_nop 0
	v_mfma_f32_32x32x16_bf16 v[64:79], v[184:187], v[188:191], v[64:79]
	ds_read_b128 v[184:187], v201 offset:20992
	ds_read_b128 v[196:199], v201 offset:22016
	s_waitcnt lgkmcnt(0)
	v_mfma_f32_32x32x16_bf16 v[48:63], v[184:187], v[188:191], v[48:63]
	ds_read_b128 v[184:187], v200 offset:24576
	v_mfma_f32_32x32x16_bf16 v[32:47], v[192:195], v[188:191], v[32:47]
	ds_read_b128 v[192:195], v200 offset:25600
	v_mfma_f32_32x32x16_bf16 v[16:31], v[196:199], v[188:191], v[16:31]
	v_cvt_pk_bf16_f32 v188, v80, v81
	v_cvt_pk_bf16_f32 v189, v82, v83
	v_cvt_pk_bf16_f32 v190, v84, v85
	v_cvt_pk_bf16_f32 v191, v86, v87
	s_waitcnt lgkmcnt(0)
	s_nop 0
	v_mfma_f32_32x32x16_bf16 v[64:79], v[184:187], v[188:191], v[64:79]
	ds_read_b128 v[184:187], v201 offset:25088
	ds_read_b128 v[196:199], v201 offset:26112
	s_waitcnt lgkmcnt(0)
	v_mfma_f32_32x32x16_bf16 v[48:63], v[184:187], v[188:191], v[48:63]
	ds_read_b128 v[184:187], v200 offset:28672
	v_mfma_f32_32x32x16_bf16 v[32:47], v[192:195], v[188:191], v[32:47]
	ds_read_b128 v[192:195], v200 offset:29696
	v_mfma_f32_32x32x16_bf16 v[16:31], v[196:199], v[188:191], v[16:31]
	v_cvt_pk_bf16_f32 v188, v88, v89
	v_cvt_pk_bf16_f32 v189, v90, v91
	v_cvt_pk_bf16_f32 v190, v92, v93
	v_cvt_pk_bf16_f32 v191, v94, v95
	s_waitcnt lgkmcnt(0)
	s_nop 0
	v_mfma_f32_32x32x16_bf16 v[64:79], v[184:187], v[188:191], v[64:79]
	ds_read_b128 v[184:187], v201 offset:29184
	ds_read_b128 v[196:199], v201 offset:30208
	s_waitcnt lgkmcnt(0)
	v_mfma_f32_32x32x16_bf16 v[48:63], v[184:187], v[188:191], v[48:63]
	v_mfma_f32_32x32x16_bf16 v[32:47], v[192:195], v[188:191], v[32:47]
	v_mfma_f32_32x32x16_bf16 v[16:31], v[196:199], v[188:191], v[16:31]
	s_cbranch_vccz .Lcj_cnt_0
	s_waitcnt vmcnt(0)
	s_branch .LBB0_1448
.Lcj_cnt_0:
	s_add_i32 s93, s88, s89
	s_add_i32 s93, s93, s90
	s_cmp_eq_u32 s93, 0
	s_cbranch_scc1 .Lcj_w6_0
	s_cmp_eq_u32 s93, 2
	s_cbranch_scc1 .Lcj_w8_0
	s_cmp_eq_u32 s93, 4
	s_cbranch_scc1 .Lcj_w10_0
	s_waitcnt vmcnt(12)
	s_branch .LBB0_1448
.Lcj_w10_0:
	s_waitcnt vmcnt(10)
	s_branch .LBB0_1448
.Lcj_w8_0:
	s_waitcnt vmcnt(8)
	s_branch .LBB0_1448
.Lcj_w6_0:
	s_waitcnt vmcnt(6)
	s_branch .LBB0_1448
.LBB0_1455:
	ds_bpermute_b32 v80, v133, v135
	s_waitcnt lgkmcnt(0)
	v_add_f32_e32 v80, v135, v80
	v_div_scale_f32 v81, s[26:27], v80, v80, 1.0
	v_rcp_f32_e32 v82, v81
	v_div_scale_f32 v83, vcc, 1.0, v80, 1.0
	s_or_b32 s26, s48, 1
	v_fma_f32 v84, -v81, v82, 1.0
	v_fmac_f32_e32 v82, v84, v82
	v_mul_f32_e32 v84, v83, v82
	v_fma_f32 v85, -v81, v84, v83
	v_fmac_f32_e32 v84, v85, v82
	v_fma_f32 v81, -v81, v84, v83
	v_div_fmas_f32 v81, v81, v82, v84
	v_div_fixup_f32 v80, v81, v80, 1.0
	v_mul_f32_e32 v64, v64, v80
	v_mul_f32_e32 v65, v65, v80
	v_mul_f32_e32 v66, v66, v80
	v_mul_f32_e32 v67, v67, v80
	v_cvt_pk_bf16_f32 v216, v64, v65
	v_cvt_pk_bf16_f32 v214, v66, v67
	v_mul_f32_e32 v64, v68, v80
	v_mul_f32_e32 v65, v69, v80
	v_mul_f32_e32 v66, v70, v80
	v_mul_f32_e32 v67, v71, v80
	v_cvt_pk_bf16_f32 v212, v64, v65
	v_cvt_pk_bf16_f32 v210, v66, v67
	v_mul_f32_e32 v64, v72, v80
	v_mul_f32_e32 v65, v73, v80
	v_mul_f32_e32 v66, v74, v80
	v_mul_f32_e32 v67, v75, v80
	v_mul_f32_e32 v48, v48, v80
	v_mul_f32_e32 v49, v49, v80
	v_mul_f32_e32 v50, v50, v80
	v_mul_f32_e32 v51, v51, v80
	v_cvt_pk_bf16_f32 v207, v64, v65
	v_cvt_pk_bf16_f32 v206, v66, v67
	v_mul_f32_e32 v64, v76, v80
	v_mul_f32_e32 v65, v77, v80
	v_mul_f32_e32 v66, v78, v80
	v_mul_f32_e32 v67, v79, v80
	v_cvt_pk_bf16_f32 v205, v64, v65
	v_cvt_pk_bf16_f32 v204, v66, v67
	v_cvt_pk_bf16_f32 v203, v48, v49
	v_cvt_pk_bf16_f32 v202, v50, v51
	v_mul_f32_e32 v48, v52, v80
	v_mul_f32_e32 v49, v53, v80
	v_mul_f32_e32 v50, v54, v80
	v_mul_f32_e32 v51, v55, v80
	v_cvt_pk_bf16_f32 v201, v48, v49
	v_cvt_pk_bf16_f32 v200, v50, v51
	v_mul_f32_e32 v48, v56, v80
	v_mul_f32_e32 v49, v57, v80
	v_mul_f32_e32 v50, v58, v80
	v_mul_f32_e32 v51, v59, v80
	v_mul_f32_e32 v32, v32, v80
	v_mul_f32_e32 v33, v33, v80
	v_mul_f32_e32 v34, v34, v80
	v_mul_f32_e32 v35, v35, v80
	v_cvt_pk_bf16_f32 v197, v48, v49
	v_cvt_pk_bf16_f32 v196, v50, v51
	v_mul_f32_e32 v48, v60, v80
	v_mul_f32_e32 v49, v61, v80
	v_mul_f32_e32 v50, v62, v80
	v_mul_f32_e32 v51, v63, v80
	v_cvt_pk_bf16_f32 v199, v48, v49
	v_cvt_pk_bf16_f32 v198, v50, v51
	v_cvt_pk_bf16_f32 v193, v32, v33
	v_cvt_pk_bf16_f32 v192, v34, v35
	v_mul_f32_e32 v32, v36, v80
	v_mul_f32_e32 v33, v37, v80
	v_mul_f32_e32 v34, v38, v80
	v_mul_f32_e32 v35, v39, v80
	v_cvt_pk_bf16_f32 v195, v32, v33
	v_cvt_pk_bf16_f32 v194, v34, v35
	v_mul_f32_e32 v32, v40, v80
	v_mul_f32_e32 v33, v41, v80
	v_mul_f32_e32 v34, v42, v80
	v_mul_f32_e32 v35, v43, v80
	v_mul_f32_e32 v16, v16, v80
	v_mul_f32_e32 v17, v17, v80
	v_cvt_pk_bf16_f32 v189, v32, v33
	v_cvt_pk_bf16_f32 v188, v34, v35
	v_mul_f32_e32 v32, v44, v80
	v_mul_f32_e32 v33, v45, v80
	v_mul_f32_e32 v34, v46, v80
	v_mul_f32_e32 v35, v47, v80
	v_cvt_pk_bf16_f32 v191, v32, v33
	v_cvt_pk_bf16_f32 v190, v34, v35
	v_cvt_pk_bf16_f32 v186, v16, v17
	v_mul_f32_e32 v16, v20, v80
	v_mul_f32_e32 v17, v21, v80
	v_mul_f32_e32 v18, v18, v80
	v_mul_f32_e32 v19, v19, v80
	v_cvt_pk_bf16_f32 v185, v18, v19
	v_cvt_pk_bf16_f32 v187, v16, v17
	v_mul_f32_e32 v16, v24, v80
	v_mul_f32_e32 v17, v25, v80
	v_mul_f32_e32 v18, v22, v80
	v_mul_f32_e32 v19, v23, v80
	v_cvt_pk_bf16_f32 v184, v18, v19
	v_cvt_pk_bf16_f32 v165, v16, v17
	v_mul_f32_e32 v16, v28, v80
	v_mul_f32_e32 v17, v29, v80
	s_mul_i32 s4, s26, 0x220000
	s_lshl_b32 s26, s26, 7
	s_mov_b32 s27, s5
	v_mul_f32_e32 v18, v26, v80
	v_mul_f32_e32 v19, v27, v80
	v_cvt_pk_bf16_f32 v164, v18, v19
	v_cvt_pk_bf16_f32 v167, v16, v17
	v_lshl_add_u64 v[16:17], v[150:151], 0, s[26:27]
	v_mov_b32_e32 v135, v131
	v_lshl_add_u64 v[16:17], v[16:17], 0, v[134:135]
	v_mul_f32_e32 v18, v30, v80
	v_mul_f32_e32 v19, v31, v80
	v_cvt_pk_bf16_f32 v166, v18, v19
	global_load_dwordx4 v[112:115], v[16:17], off
	global_load_dwordx4 v[116:119], v[16:17], off offset:32
	global_load_dwordx4 v[120:123], v[16:17], off offset:64
	global_load_dwordx4 v[124:127], v[16:17], off offset:96
	v_lshl_add_u64 v[16:17], v[140:141], 0, s[4:5]
	v_readfirstlane_b32 s4, v182
	v_lshl_add_u64 v[18:19], v[16:17], 0, s[16:17]
	s_mov_b32 m0, s4
	v_readfirstlane_b32 s4, v209
	s_waitcnt vmcnt(0)
	s_barrier
	global_load_lds_dwordx4 v[18:19], off
	s_mov_b32 m0, s4
	v_readfirstlane_b32 s4, v211
	global_load_lds_dwordx4 v[152:153], off
	s_mov_b32 m0, s4
	v_readfirstlane_b32 s4, v213
	global_load_lds_dwordx4 v[154:155], off
	v_lshl_add_u64 v[18:19], v[16:17], 0, s[18:19]
	s_mov_b32 m0, s4
	v_readfirstlane_b32 s4, v215
	global_load_lds_dwordx4 v[18:19], off
	s_mov_b32 m0, s4
	v_readfirstlane_b32 s4, v217
	global_load_lds_dwordx4 v[156:157], off
	s_mov_b32 m0, s4
	v_readfirstlane_b32 s4, v218
	global_load_lds_dwordx4 v[158:159], off
	v_lshl_add_u64 v[16:17], v[16:17], 0, s[22:23]
	s_mov_b32 m0, s4
	v_readfirstlane_b32 s4, v219
	global_load_lds_dwordx4 v[16:17], off
	s_mov_b32 m0, s4
	v_readfirstlane_b32 s4, v220
	global_load_lds_dwordx4 v[160:161], off
	s_mov_b32 m0, s4
	v_mov_b32_e32 v135, 0
	global_load_lds_dwordx4 v[162:163], off
	s_waitcnt vmcnt(6)
	v_lshl_add_u64 v[150:151], v[146:147], 0, s[24:25]
	s_mov_b32 s4, 0
	s_mov_b32 s22, 0x18000
	v_mov_b32_e32 v64, 0
	v_mov_b32_e32 v65, v135
	v_mov_b32_e32 v66, v135
	v_mov_b32_e32 v67, v135
	v_mov_b32_e32 v68, v135
	v_mov_b32_e32 v69, v135
	v_mov_b32_e32 v70, v135
	v_mov_b32_e32 v71, v135
	v_mov_b32_e32 v72, v135
	v_mov_b32_e32 v73, v135
	v_mov_b32_e32 v74, v135
	v_mov_b32_e32 v75, v135
	v_mov_b32_e32 v76, v135
	v_mov_b32_e32 v77, v135
	v_mov_b32_e32 v78, v135
	v_mov_b32_e32 v79, v135
	v_mov_b32_e32 v48, 0
	v_mov_b32_e32 v49, v135
	v_mov_b32_e32 v50, v135
	v_mov_b32_e32 v51, v135
	v_mov_b32_e32 v52, v135
	v_mov_b32_e32 v53, v135
	v_mov_b32_e32 v54, v135
	v_mov_b32_e32 v55, v135
	v_mov_b32_e32 v56, v135
	v_mov_b32_e32 v57, v135
	v_mov_b32_e32 v58, v135
	v_mov_b32_e32 v59, v135
	v_mov_b32_e32 v60, v135
	v_mov_b32_e32 v61, v135
	v_mov_b32_e32 v62, v135
	v_mov_b32_e32 v63, v135
	v_mov_b32_e32 v32, 0
	v_mov_b32_e32 v33, v135
	v_mov_b32_e32 v34, v135
	v_mov_b32_e32 v35, v135
	v_mov_b32_e32 v36, v135
	v_mov_b32_e32 v37, v135
	v_mov_b32_e32 v38, v135
	v_mov_b32_e32 v39, v135
	v_mov_b32_e32 v40, v135
	v_mov_b32_e32 v41, v135
	v_mov_b32_e32 v42, v135
	v_mov_b32_e32 v43, v135
	v_mov_b32_e32 v44, v135
	v_mov_b32_e32 v45, v135
	v_mov_b32_e32 v46, v135
	v_mov_b32_e32 v47, v135
	v_mov_b32_e32 v16, 0
	v_mov_b32_e32 v17, v135
	v_mov_b32_e32 v18, v135
	v_mov_b32_e32 v19, v135
	v_mov_b32_e32 v20, v135
	v_mov_b32_e32 v21, v135
	v_mov_b32_e32 v22, v135
	v_mov_b32_e32 v23, v135
	v_mov_b32_e32 v24, v135
	v_mov_b32_e32 v25, v135
	v_mov_b32_e32 v26, v135
	v_mov_b32_e32 v27, v135
	v_mov_b32_e32 v28, v135
	v_mov_b32_e32 v29, v135
	v_mov_b32_e32 v30, v135
	v_mov_b32_e32 v31, v135
	s_barrier
	s_mov_b32 s90, 0
	s_mov_b32 s88, 0
	s_mov_b32 s89, 0
	s_lshr_b32 s91, s2, 7
	s_lshl_b32 s92, s98, 1
	s_add_i32 s91, s91, s92
	s_mul_i32 s92, s91, 0xab
	s_lshr_b32 s92, s92, 9
	s_mul_i32 s93, s92, 3
	s_sub_i32 s91, s91, s93
	v_mbcnt_lo_u32_b32 v222, -1, 0
	v_mbcnt_hi_u32_b32 v222, -1, v222
	s_and_b32 s93, s2, 0x7f
	s_lshl_b32 s93, s93, 9
	s_or_b32 s93, s93, s63
	v_or_b32_e32 v222, s93, v222
	s_cmp_eq_u32 s91, 2
	s_cselect_b32 s93, 12, 11
	v_lshrrev_b32_e32 v223, s93, v222
	v_and_b32_e32 v208, 7, v222
	v_lshl_or_b32 v223, v223, 3, v208
	s_cselect_b32 s93, 6, 5
	v_bfe_u32 v208, v222, 6, s93
	v_lshrrev_b32_e32 v222, 1, v222
	v_and_b32_e32 v222, 28, v222
	v_lshl_or_b32 v222, v208, 5, v222
	v_lshlrev_b32_e32 v222, 2, v222
	s_cselect_b32 s93, 16, 15
	v_lshlrev_b32_e32 v223, s93, v223
	v_add_u32_e32 v222, v223, v222
	s_cselect_b32 s94, 1, 0
	s_lshl_b32 s94, 0x1000, s94
	s_lshl_b32 s92, s92, 23
	s_cmp_eq_u32 s91, 0
	s_cselect_b64 s[100:101], s[76:77], s[78:79]
	s_cmp_eq_u32 s91, 2
	s_cselect_b64 s[100:101], s[80:81], s[100:101]
	s_add_u32 s100, s100, s92
	s_addc_u32 s101, s101, 0
	s_mov_b32 s95, 1
	s_branch .LBB0_1457

.Lcj_common_1:
	s_waitcnt lgkmcnt(0)
	s_mov_b32 s89, s88
	s_mov_b32 s88, s90
	s_mov_b32 s90, 0
	s_add_i32 s4, s4, 1
	s_add_i32 s22, s22, 0x8000
	v_lshl_add_u64 v[148:149], v[148:149], 0, s[12:13]
	v_lshl_add_u64 v[150:151], v[150:151], 0, s[10:11]
	s_cmp_lg_u32 s22, 0x238000
	s_barrier
	s_cbranch_scc0 .LBB0_1446
.LBB0_1457:
	s_cmp_gt_u32 s4, 64
	s_cselect_b64 s[16:17], -1, 0
	s_and_b64 vcc, exec, s[16:17]
	s_cbranch_vccnz .LBB0_1459
	s_and_b32 s18, s22, 0x18000
	v_add_u32_e32 v82, s18, v182
	v_add_u32_e32 v80, 0x4000, v82
	v_readfirstlane_b32 s18, v82
	s_mov_b32 m0, s18
	v_readfirstlane_b32 s18, v80
	v_add_u32_e32 v82, 0x6000, v82
	global_load_lds_dwordx4 v[150:151], off
	s_mov_b32 m0, s18
	v_readfirstlane_b32 s18, v82
	global_load_lds_dwordx4 v[148:149], off
	v_lshl_add_u64 v[80:81], v[148:149], 0, s[10:11]
	s_mov_b32 m0, s18
	s_nop 0
	global_load_lds_dwordx4 v[80:81], off

.Lcjh_done_1:
	s_add_i32 s18, s22, 0xfffe8000
	s_and_b32 s18, s18, 0x18000
	s_add_i32 s18, s18, 0
	v_add3_u32 v84, s18, v177, v176
	ds_read_b128 v[80:83], v84
	ds_read_b128 v[152:155], v84 offset:512
	v_add3_u32 v85, s18, v178, v176
	v_add3_u32 v84, s18, v179, v176
	v_add_u32_e32 v209, s18, v168
	v_add_u32_e32 v211, s18, v169
	s_and_b64 vcc, exec, s[16:17]
	s_waitcnt lgkmcnt(0)
	v_mfma_f32_32x32x16_bf16 v[96:111], v[80:83], v[112:115], v[0:15]
	ds_read_b128 v[80:83], v85 offset:2048
	ds_read_b128 v[156:159], v85 offset:2560
	v_add3_u32 v85, s18, v180, v176
	s_mov_b64 s[18:19], -1
	ds_read_b128 v[160:163], v84 offset:4608
	s_waitcnt lgkmcnt(0)
	v_mfma_f32_32x32x16_bf16 v[96:111], v[80:83], v[116:119], v[96:111]
	ds_read_b128 v[80:83], v84 offset:4096
	s_waitcnt lgkmcnt(0)
	v_mfma_f32_32x32x16_bf16 v[96:111], v[80:83], v[120:123], v[96:111]
	ds_read_b128 v[80:83], v85 offset:6144
	ds_read_b128 v[218:221], v85 offset:6656
	s_waitcnt lgkmcnt(0)
	v_mfma_f32_32x32x16_bf16 v[96:111], v[80:83], v[124:127], v[96:111]
	v_mfma_f32_32x32x16_bf16 v[80:95], v[152:155], v[112:115], v[0:15]
	ds_read_b128 v[152:155], v209 offset:16384
	s_nop 9
	v_exp_f32_e32 v96, v96
	v_exp_f32_e32 v97, v97
	v_exp_f32_e32 v98, v98
	v_exp_f32_e32 v99, v99
	v_exp_f32_e32 v100, v100
	v_exp_f32_e32 v101, v101
	v_mfma_f32_32x32x16_bf16 v[80:95], v[156:159], v[116:119], v[80:95]
	v_exp_f32_e32 v102, v102
	v_exp_f32_e32 v103, v103
	v_cvt_pk_bf16_f32 v156, v96, v97
	v_cvt_pk_bf16_f32 v157, v98, v99
	v_cvt_pk_bf16_f32 v158, v100, v101
	v_cvt_pk_bf16_f32 v159, v102, v103
	v_exp_f32_e32 v104, v104
	v_mfma_f32_32x32x16_bf16 v[80:95], v[160:163], v[120:123], v[80:95]
	ds_read_b128 v[160:163], v209 offset:17408
	v_exp_f32_e32 v105, v105
	v_exp_f32_e32 v106, v106
	v_exp_f32_e32 v107, v107
	v_exp_f32_e32 v108, v108
	v_exp_f32_e32 v109, v109
	v_exp_f32_e32 v110, v110
	v_mfma_f32_32x32x16_bf16 v[80:95], v[218:221], v[124:127], v[80:95]
	v_exp_f32_e32 v111, v111
	s_waitcnt lgkmcnt(0)
	v_mfma_f32_32x32x16_bf16 v[64:79], v[152:155], v[156:159], v[64:79]
	ds_read_b128 v[152:155], v211 offset:16896
	ds_read_b128 v[218:221], v211 offset:17920
	s_nop 6
	v_exp_f32_e32 v80, v80
	v_exp_f32_e32 v81, v81
	v_exp_f32_e32 v82, v82
	v_exp_f32_e32 v83, v83
	v_exp_f32_e32 v84, v84
	v_exp_f32_e32 v85, v85
	s_waitcnt lgkmcnt(0)
	v_mfma_f32_32x32x16_bf16 v[48:63], v[152:155], v[156:159], v[48:63]
	ds_read_b128 v[152:155], v209 offset:20480
	v_exp_f32_e32 v86, v86
	v_exp_f32_e32 v87, v87
	v_exp_f32_e32 v88, v88
	v_exp_f32_e32 v89, v89
	v_exp_f32_e32 v90, v90
	v_exp_f32_e32 v91, v91
	v_mfma_f32_32x32x16_bf16 v[32:47], v[160:163], v[156:159], v[32:47]
	ds_read_b128 v[160:163], v209 offset:21504
	v_exp_f32_e32 v92, v92
	v_exp_f32_e32 v93, v93
	v_exp_f32_e32 v94, v94
	v_exp_f32_e32 v95, v95
	v_mfma_f32_32x32x16_bf16 v[16:31], v[218:221], v[156:159], v[16:31]
	v_cvt_pk_bf16_f32 v156, v104, v105
	v_cvt_pk_bf16_f32 v157, v106, v107
	v_cvt_pk_bf16_f32 v158, v108, v109
	v_cvt_pk_bf16_f32 v159, v110, v111
	s_waitcnt lgkmcnt(0)
	s_nop 0
	v_mfma_f32_32x32x16_bf16 v[64:79], v[152:155], v[156:159], v[64:79]
	ds_read_b128 v[152:155], v211 offset:20992
	ds_read_b128 v[218:221], v211 offset:22016
	s_waitcnt lgkmcnt(0)
	v_mfma_f32_32x32x16_bf16 v[48:63], v[152:155], v[156:159], v[48:63]
	ds_read_b128 v[152:155], v209 offset:24576
	v_mfma_f32_32x32x16_bf16 v[32:47], v[160:163], v[156:159], v[32:47]
	ds_read_b128 v[160:163], v209 offset:25600
	v_mfma_f32_32x32x16_bf16 v[16:31], v[218:221], v[156:159], v[16:31]
	v_cvt_pk_bf16_f32 v156, v80, v81
	v_cvt_pk_bf16_f32 v157, v82, v83
	v_cvt_pk_bf16_f32 v158, v84, v85
	v_cvt_pk_bf16_f32 v159, v86, v87
	s_waitcnt lgkmcnt(0)
	s_nop 0
	v_mfma_f32_32x32x16_bf16 v[64:79], v[152:155], v[156:159], v[64:79]
	ds_read_b128 v[152:155], v211 offset:25088
	ds_read_b128 v[218:221], v211 offset:26112
	s_waitcnt lgkmcnt(0)
	v_mfma_f32_32x32x16_bf16 v[48:63], v[152:155], v[156:159], v[48:63]
	ds_read_b128 v[152:155], v209 offset:28672
	v_mfma_f32_32x32x16_bf16 v[32:47], v[160:163], v[156:159], v[32:47]
	ds_read_b128 v[160:163], v209 offset:29696
	v_mfma_f32_32x32x16_bf16 v[16:31], v[218:221], v[156:159], v[16:31]
	v_cvt_pk_bf16_f32 v156, v88, v89
	v_cvt_pk_bf16_f32 v157, v90, v91
	v_cvt_pk_bf16_f32 v158, v92, v93
	v_cvt_pk_bf16_f32 v159, v94, v95
	s_waitcnt lgkmcnt(0)
	s_nop 0
	v_mfma_f32_32x32x16_bf16 v[64:79], v[152:155], v[156:159], v[64:79]
	ds_read_b128 v[152:155], v211 offset:29184
	ds_read_b128 v[218:221], v211 offset:30208
	s_waitcnt lgkmcnt(0)
	v_mfma_f32_32x32x16_bf16 v[48:63], v[152:155], v[156:159], v[48:63]
	v_mfma_f32_32x32x16_bf16 v[32:47], v[160:163], v[156:159], v[32:47]
	v_mfma_f32_32x32x16_bf16 v[16:31], v[218:221], v[156:159], v[16:31]
	s_cbranch_vccz .Lcj_cnt_1
	s_waitcnt vmcnt(0)
	s_branch .LBB0_1456

	.amdhsa_kernel _Z4mega6Params
		.amdhsa_group_segment_fixed_size 0
		.amdhsa_private_segment_fixed_size 0
		.amdhsa_kernarg_size 816
		.amdhsa_user_sgpr_count 2
		.amdhsa_user_sgpr_dispatch_ptr 0
		.amdhsa_user_sgpr_queue_ptr 0
		.amdhsa_user_sgpr_kernarg_segment_ptr 1
		.amdhsa_user_sgpr_dispatch_id 0
		.amdhsa_user_sgpr_kernarg_preload_length 0
		.amdhsa_user_sgpr_kernarg_preload_offset 0
		.amdhsa_user_sgpr_private_segment_size 0
		.amdhsa_uses_dynamic_stack 0
		.amdhsa_enable_private_segment 0
		.amdhsa_system_sgpr_workgroup_id_x 1
		.amdhsa_system_sgpr_workgroup_id_y 0
		.amdhsa_system_sgpr_workgroup_id_z 0
		.amdhsa_system_sgpr_workgroup_info 0
		.amdhsa_system_vgpr_workitem_id 0
		.amdhsa_next_free_vgpr 256
		.amdhsa_next_free_sgpr 102
		.amdhsa_accum_offset 256
		.amdhsa_reserve_vcc 1
		.amdhsa_float_round_mode_32 0
		.amdhsa_float_round_mode_16_64 0
		.amdhsa_float_denorm_mode_32 3
		.amdhsa_float_denorm_mode_16_64 3
		.amdhsa_dx10_clamp 1
		.amdhsa_ieee_mode 1
		.amdhsa_fp16_overflow 0
		.amdhsa_tg_split 0
		.amdhsa_exception_fp_ieee_invalid_op 0
		.amdhsa_exception_fp_denorm_src 0
		.amdhsa_exception_fp_ieee_div_zero 0
		.amdhsa_exception_fp_ieee_overflow 0
		.amdhsa_exception_fp_ieee_underflow 0
		.amdhsa_exception_fp_ieee_inexact 0
		.amdhsa_exception_int_div_zero 0
	.end_amdhsa_kernel

amdhsa.kernels:
  - .agpr_count:     0
    .args:
      - .offset:         0
        .size:           560
        .value_kind:     by_value
      - .offset:         560
        .size:           4
        .value_kind:     hidden_block_count_x
      - .offset:         564
        .size:           4
        .value_kind:     hidden_block_count_y
      - .offset:         568
        .size:           4
        .value_kind:     hidden_block_count_z
      - .offset:         572
        .size:           2
        .value_kind:     hidden_group_size_x
      - .offset:         574
        .size:           2
        .value_kind:     hidden_group_size_y
      - .offset:         576
        .size:           2
        .value_kind:     hidden_group_size_z
      - .offset:         578
        .size:           2
        .value_kind:     hidden_remainder_x
      - .offset:         580
        .size:           2
        .value_kind:     hidden_remainder_y
      - .offset:         582
        .size:           2
        .value_kind:     hidden_remainder_z
      - .offset:         600
        .size:           8
        .value_kind:     hidden_global_offset_x
      - .offset:         608
        .size:           8
        .value_kind:     hidden_global_offset_y
      - .offset:         616
        .size:           8
        .value_kind:     hidden_global_offset_z
      - .offset:         624
        .size:           2
        .value_kind:     hidden_grid_dims
      - .offset:         680
        .size:           4
        .value_kind:     hidden_dynamic_lds_size
    .group_segment_fixed_size: 0
    .kernarg_segment_align: 8
    .kernarg_segment_size: 816
    .language:       OpenCL C
    .language_version:
      - 2
      - 0
    .max_flat_workgroup_size: 512
    .name:           _Z4mega6Params
    .private_segment_fixed_size: 0
    .sgpr_count:     108
    .sgpr_spill_count: 3
    .symbol:         _Z4mega6Params.kd
    .uniform_work_group_size: 1
    .uses_dynamic_stack: false
    .vgpr_count:     256
    .vgpr_spill_count: 0
    .wavefront_size: 64
